# hand-written RWKV scan-wave step (56 VALU/step, software-pipelined y reduction) + helper-wave global loads de-serialised (conversions moved to consumers)
# speedup vs baseline: 1.0379x; 1.0379x over previous
.LBB0_390:
	s_and_b32 s3, s2, 1
	s_mul_i32 s8, s3, 0x5000
	v_add_u32_e32 v2, s8, v136
	s_mul_i32 s8, s2, 0xab
	s_bfe_u32 s8, s8, 0x70009
	s_mul_i32 s8, s8, 3
	s_sub_i32 s8, s2, s8
	s_and_b32 s8, s8, 0xff
	s_mulk_i32 s8, 0x1100
	v_add_u32_e32 v3, s8, v137
	v_lshl_add_u32 v1, s3, 12, v137
	ds_read_b128 v[176:179], v2 offset:4096
	ds_read_b128 v[180:183], v2 offset:4112
	ds_read_b128 v[200:203], v2 offset:12288
	ds_read_b128 v[204:207], v2 offset:12304
	ds_read_b64 v[216:217], v3 offset:40960
	ds_read_b128 v[184:187], v2 offset:0
	ds_read_b128 v[188:191], v2 offset:16
	ds_read_b128 v[192:195], v2 offset:8192
	ds_read_b128 v[196:199], v2 offset:8208
	s_waitcnt lgkmcnt(8)
	v_pk_mul_f32 v[164:165], v[72:73], v[176:177]
	v_pk_mul_f32 v[166:167], v[80:81], v[176:177]
	v_pk_fma_f32 v[164:165], v[74:75], v[178:179], v[164:165]
	v_pk_fma_f32 v[166:167], v[82:83], v[178:179], v[166:167]
	s_waitcnt lgkmcnt(7)
	v_pk_fma_f32 v[164:165], v[76:77], v[180:181], v[164:165]
	v_pk_fma_f32 v[166:167], v[84:85], v[180:181], v[166:167]
	v_pk_fma_f32 v[164:165], v[78:79], v[182:183], v[164:165]
	v_pk_fma_f32 v[166:167], v[86:87], v[182:183], v[166:167]
	ds_read_b128 v[176:179], v2 offset:4352
	ds_read_b128 v[180:183], v2 offset:4368
	ds_read_b128 v[208:211], v2 offset:16384
	ds_read_b128 v[212:215], v2 offset:16400
	s_waitcnt lgkmcnt(8)
	v_pk_mul_f32 v[218:219], v[216:217], v[200:201] op_sel_hi:[0,1]
	v_pk_mul_f32 v[226:227], v[216:217], v[200:201] op_sel:[1,0]
	v_pk_mul_f32 v[220:221], v[216:217], v[202:203] op_sel_hi:[0,1]
	v_pk_mul_f32 v[228:229], v[216:217], v[202:203] op_sel:[1,0]
	v_pk_mul_f32 v[222:223], v[216:217], v[204:205] op_sel_hi:[0,1]
	v_pk_mul_f32 v[230:231], v[216:217], v[204:205] op_sel:[1,0]
	v_pk_mul_f32 v[224:225], v[216:217], v[206:207] op_sel_hi:[0,1]
	v_pk_mul_f32 v[234:235], v[216:217], v[206:207] op_sel:[1,0]
	ds_read_b128 v[200:203], v2 offset:12544
	ds_read_b128 v[204:207], v2 offset:12560
	ds_read_b64 v[216:217], v3 offset:41216
	v_add_f32_e32 v172, v164, v165
	v_add_f32_e32 v174, v166, v167
	s_waitcnt lgkmcnt(10)
	v_pk_fma_f32 v[218:219], v[72:73], v[184:185], v[218:219]
	v_pk_fma_f32 v[226:227], v[80:81], v[184:185], v[226:227]
	v_pk_fma_f32 v[220:221], v[74:75], v[186:187], v[220:221]
	v_pk_fma_f32 v[228:229], v[82:83], v[186:187], v[228:229]
	v_add_f32_dpp v172, v172, v172 quad_perm:[1,0,3,2] row_mask:0xf bank_mask:0xf bound_ctrl:1
	v_add_f32_dpp v174, v174, v174 quad_perm:[1,0,3,2] row_mask:0xf bank_mask:0xf bound_ctrl:1
	s_waitcnt lgkmcnt(9)
	v_pk_fma_f32 v[222:223], v[76:77], v[188:189], v[222:223]
	v_pk_fma_f32 v[230:231], v[84:85], v[188:189], v[230:231]
	v_pk_fma_f32 v[224:225], v[78:79], v[190:191], v[224:225]
	v_pk_fma_f32 v[234:235], v[86:87], v[190:191], v[234:235]
	ds_read_b128 v[184:187], v2 offset:256
	ds_read_b128 v[188:191], v2 offset:272
	v_add_f32_dpp v172, v172, v172 quad_perm:[2,3,0,1] row_mask:0xf bank_mask:0xf bound_ctrl:1
	v_add_f32_dpp v174, v174, v174 quad_perm:[2,3,0,1] row_mask:0xf bank_mask:0xf bound_ctrl:1
	s_nop 0
	v_add_f32_dpp v172, v172, v172 row_half_mirror row_mask:0xf bank_mask:0xf bound_ctrl:1
	v_add_f32_dpp v174, v174, v174 row_half_mirror row_mask:0xf bank_mask:0xf bound_ctrl:1
	s_nop 1
	s_waitcnt lgkmcnt(10)
	v_pk_fma_f32 v[72:73], v[192:193], v[172:173], v[218:219] op_sel_hi:[1,0,1]
	v_pk_fma_f32 v[80:81], v[192:193], v[174:175], v[226:227] op_sel_hi:[1,0,1]
	v_pk_fma_f32 v[74:75], v[194:195], v[172:173], v[220:221] op_sel_hi:[1,0,1]
	v_pk_fma_f32 v[82:83], v[194:195], v[174:175], v[228:229] op_sel_hi:[1,0,1]
	s_waitcnt lgkmcnt(9)
	v_pk_fma_f32 v[76:77], v[196:197], v[172:173], v[222:223] op_sel_hi:[1,0,1]
	v_pk_fma_f32 v[84:85], v[196:197], v[174:175], v[230:231] op_sel_hi:[1,0,1]
	v_pk_fma_f32 v[78:79], v[198:199], v[172:173], v[224:225] op_sel_hi:[1,0,1]
	v_pk_fma_f32 v[86:87], v[198:199], v[174:175], v[234:235] op_sel_hi:[1,0,1]
	ds_read_b128 v[192:195], v2 offset:8448
	ds_read_b128 v[196:199], v2 offset:8464
	s_waitcnt lgkmcnt(10)
	v_pk_mul_f32 v[164:165], v[72:73], v[176:177]
	v_pk_mul_f32 v[166:167], v[80:81], v[176:177]
	s_waitcnt lgkmcnt(8)
	v_pk_mul_f32 v[168:169], v[72:73], v[208:209]
	v_pk_mul_f32 v[170:171], v[80:81], v[208:209]
	v_pk_fma_f32 v[164:165], v[74:75], v[178:179], v[164:165]
	v_pk_fma_f32 v[166:167], v[82:83], v[178:179], v[166:167]
	v_pk_fma_f32 v[168:169], v[74:75], v[210:211], v[168:169]
	v_pk_fma_f32 v[170:171], v[82:83], v[210:211], v[170:171]
	v_pk_fma_f32 v[164:165], v[76:77], v[180:181], v[164:165]
	v_pk_fma_f32 v[166:167], v[84:85], v[180:181], v[166:167]
	s_waitcnt lgkmcnt(7)
	v_pk_fma_f32 v[168:169], v[76:77], v[212:213], v[168:169]
	v_pk_fma_f32 v[170:171], v[84:85], v[212:213], v[170:171]
	v_pk_fma_f32 v[164:165], v[78:79], v[182:183], v[164:165]
	v_pk_fma_f32 v[166:167], v[86:87], v[182:183], v[166:167]
	v_pk_fma_f32 v[168:169], v[78:79], v[214:215], v[168:169]
	v_pk_fma_f32 v[170:171], v[86:87], v[214:215], v[170:171]
	ds_read_b128 v[176:179], v2 offset:4608
	ds_read_b128 v[180:183], v2 offset:4624
	ds_read_b128 v[208:211], v2 offset:16640
	ds_read_b128 v[212:215], v2 offset:16656
	s_waitcnt lgkmcnt(8)
	v_pk_mul_f32 v[218:219], v[216:217], v[200:201] op_sel_hi:[0,1]
	v_pk_mul_f32 v[226:227], v[216:217], v[200:201] op_sel:[1,0]
	v_pk_mul_f32 v[220:221], v[216:217], v[202:203] op_sel_hi:[0,1]
	v_pk_mul_f32 v[228:229], v[216:217], v[202:203] op_sel:[1,0]
	v_pk_mul_f32 v[222:223], v[216:217], v[204:205] op_sel_hi:[0,1]
	v_pk_mul_f32 v[230:231], v[216:217], v[204:205] op_sel:[1,0]
	v_pk_mul_f32 v[224:225], v[216:217], v[206:207] op_sel_hi:[0,1]
	v_pk_mul_f32 v[234:235], v[216:217], v[206:207] op_sel:[1,0]
	ds_read_b128 v[200:203], v2 offset:12800
	ds_read_b128 v[204:207], v2 offset:12816
	ds_read_b64 v[216:217], v3 offset:41472
	v_add_f32_e32 v172, v164, v165
	v_add_f32_e32 v174, v166, v167
	v_add_f32_e32 v160, v168, v169
	v_add_f32_e32 v161, v170, v171
	s_waitcnt lgkmcnt(10)
	v_pk_fma_f32 v[218:219], v[72:73], v[184:185], v[218:219]
	v_pk_fma_f32 v[226:227], v[80:81], v[184:185], v[226:227]
	v_pk_fma_f32 v[220:221], v[74:75], v[186:187], v[220:221]
	v_pk_fma_f32 v[228:229], v[82:83], v[186:187], v[228:229]
	v_add_f32_dpp v172, v172, v172 quad_perm:[1,0,3,2] row_mask:0xf bank_mask:0xf bound_ctrl:1
	v_add_f32_dpp v174, v174, v174 quad_perm:[1,0,3,2] row_mask:0xf bank_mask:0xf bound_ctrl:1
	v_add_f32_dpp v160, v160, v160 quad_perm:[1,0,3,2] row_mask:0xf bank_mask:0xf bound_ctrl:1
	v_add_f32_dpp v161, v161, v161 quad_perm:[1,0,3,2] row_mask:0xf bank_mask:0xf bound_ctrl:1
	s_waitcnt lgkmcnt(9)
	v_pk_fma_f32 v[222:223], v[76:77], v[188:189], v[222:223]
	v_pk_fma_f32 v[230:231], v[84:85], v[188:189], v[230:231]
	v_pk_fma_f32 v[224:225], v[78:79], v[190:191], v[224:225]
	v_pk_fma_f32 v[234:235], v[86:87], v[190:191], v[234:235]
	ds_read_b128 v[184:187], v2 offset:512
	ds_read_b128 v[188:191], v2 offset:528
	v_add_f32_dpp v172, v172, v172 quad_perm:[2,3,0,1] row_mask:0xf bank_mask:0xf bound_ctrl:1
	v_add_f32_dpp v174, v174, v174 quad_perm:[2,3,0,1] row_mask:0xf bank_mask:0xf bound_ctrl:1
	v_add_f32_dpp v160, v160, v160 quad_perm:[2,3,0,1] row_mask:0xf bank_mask:0xf bound_ctrl:1
	v_add_f32_dpp v161, v161, v161 quad_perm:[2,3,0,1] row_mask:0xf bank_mask:0xf bound_ctrl:1
	v_add_f32_dpp v172, v172, v172 row_half_mirror row_mask:0xf bank_mask:0xf bound_ctrl:1
	v_add_f32_dpp v174, v174, v174 row_half_mirror row_mask:0xf bank_mask:0xf bound_ctrl:1
	v_add_f32_dpp v160, v160, v160 row_half_mirror row_mask:0xf bank_mask:0xf bound_ctrl:1
	v_add_f32_dpp v161, v161, v161 row_half_mirror row_mask:0xf bank_mask:0xf bound_ctrl:1
	s_waitcnt lgkmcnt(10)
	v_pk_fma_f32 v[72:73], v[192:193], v[172:173], v[218:219] op_sel_hi:[1,0,1]
	v_pk_fma_f32 v[80:81], v[192:193], v[174:175], v[226:227] op_sel_hi:[1,0,1]
	v_pk_fma_f32 v[74:75], v[194:195], v[172:173], v[220:221] op_sel_hi:[1,0,1]
	v_pk_fma_f32 v[82:83], v[194:195], v[174:175], v[228:229] op_sel_hi:[1,0,1]
	s_waitcnt lgkmcnt(9)
	v_pk_fma_f32 v[76:77], v[196:197], v[172:173], v[222:223] op_sel_hi:[1,0,1]
	v_pk_fma_f32 v[84:85], v[196:197], v[174:175], v[230:231] op_sel_hi:[1,0,1]
	v_pk_fma_f32 v[78:79], v[198:199], v[172:173], v[224:225] op_sel_hi:[1,0,1]
	v_pk_fma_f32 v[86:87], v[198:199], v[174:175], v[234:235] op_sel_hi:[1,0,1]
	ds_read_b128 v[192:195], v2 offset:8704
	ds_read_b128 v[196:199], v2 offset:8720
	ds_write_b64 v1, v[160:161] offset:54016
	s_waitcnt lgkmcnt(11)
	v_pk_mul_f32 v[164:165], v[72:73], v[176:177]
	v_pk_mul_f32 v[166:167], v[80:81], v[176:177]
	s_waitcnt lgkmcnt(9)
	v_pk_mul_f32 v[168:169], v[72:73], v[208:209]
	v_pk_mul_f32 v[170:171], v[80:81], v[208:209]
	v_pk_fma_f32 v[164:165], v[74:75], v[178:179], v[164:165]
	v_pk_fma_f32 v[166:167], v[82:83], v[178:179], v[166:167]
	v_pk_fma_f32 v[168:169], v[74:75], v[210:211], v[168:169]
	v_pk_fma_f32 v[170:171], v[82:83], v[210:211], v[170:171]
	v_pk_fma_f32 v[164:165], v[76:77], v[180:181], v[164:165]
	v_pk_fma_f32 v[166:167], v[84:85], v[180:181], v[166:167]
	s_waitcnt lgkmcnt(8)
	v_pk_fma_f32 v[168:169], v[76:77], v[212:213], v[168:169]
	v_pk_fma_f32 v[170:171], v[84:85], v[212:213], v[170:171]
	v_pk_fma_f32 v[164:165], v[78:79], v[182:183], v[164:165]
	v_pk_fma_f32 v[166:167], v[86:87], v[182:183], v[166:167]
	v_pk_fma_f32 v[168:169], v[78:79], v[214:215], v[168:169]
	v_pk_fma_f32 v[170:171], v[86:87], v[214:215], v[170:171]
	ds_read_b128 v[176:179], v2 offset:4864
	ds_read_b128 v[180:183], v2 offset:4880
	ds_read_b128 v[208:211], v2 offset:16896
	ds_read_b128 v[212:215], v2 offset:16912
	s_waitcnt lgkmcnt(9)
	v_pk_mul_f32 v[218:219], v[216:217], v[200:201] op_sel_hi:[0,1]
	v_pk_mul_f32 v[226:227], v[216:217], v[200:201] op_sel:[1,0]
	v_pk_mul_f32 v[220:221], v[216:217], v[202:203] op_sel_hi:[0,1]
	v_pk_mul_f32 v[228:229], v[216:217], v[202:203] op_sel:[1,0]
	v_pk_mul_f32 v[222:223], v[216:217], v[204:205] op_sel_hi:[0,1]
	v_pk_mul_f32 v[230:231], v[216:217], v[204:205] op_sel:[1,0]
	v_pk_mul_f32 v[224:225], v[216:217], v[206:207] op_sel_hi:[0,1]
	v_pk_mul_f32 v[234:235], v[216:217], v[206:207] op_sel:[1,0]
	ds_read_b128 v[200:203], v2 offset:13056
	ds_read_b128 v[204:207], v2 offset:13072
	ds_read_b64 v[216:217], v3 offset:41728
	v_add_f32_e32 v172, v164, v165
	v_add_f32_e32 v174, v166, v167
	v_add_f32_e32 v160, v168, v169
	v_add_f32_e32 v161, v170, v171
	s_waitcnt lgkmcnt(11)
	v_pk_fma_f32 v[218:219], v[72:73], v[184:185], v[218:219]
	v_pk_fma_f32 v[226:227], v[80:81], v[184:185], v[226:227]
	v_pk_fma_f32 v[220:221], v[74:75], v[186:187], v[220:221]
	v_pk_fma_f32 v[228:229], v[82:83], v[186:187], v[228:229]
	v_add_f32_dpp v172, v172, v172 quad_perm:[1,0,3,2] row_mask:0xf bank_mask:0xf bound_ctrl:1
	v_add_f32_dpp v174, v174, v174 quad_perm:[1,0,3,2] row_mask:0xf bank_mask:0xf bound_ctrl:1
	v_add_f32_dpp v160, v160, v160 quad_perm:[1,0,3,2] row_mask:0xf bank_mask:0xf bound_ctrl:1
	v_add_f32_dpp v161, v161, v161 quad_perm:[1,0,3,2] row_mask:0xf bank_mask:0xf bound_ctrl:1
	s_waitcnt lgkmcnt(10)
	v_pk_fma_f32 v[222:223], v[76:77], v[188:189], v[222:223]
	v_pk_fma_f32 v[230:231], v[84:85], v[188:189], v[230:231]
	v_pk_fma_f32 v[224:225], v[78:79], v[190:191], v[224:225]
	v_pk_fma_f32 v[234:235], v[86:87], v[190:191], v[234:235]
	ds_read_b128 v[184:187], v2 offset:768
	ds_read_b128 v[188:191], v2 offset:784
	v_add_f32_dpp v172, v172, v172 quad_perm:[2,3,0,1] row_mask:0xf bank_mask:0xf bound_ctrl:1
	v_add_f32_dpp v174, v174, v174 quad_perm:[2,3,0,1] row_mask:0xf bank_mask:0xf bound_ctrl:1
	v_add_f32_dpp v160, v160, v160 quad_perm:[2,3,0,1] row_mask:0xf bank_mask:0xf bound_ctrl:1
	v_add_f32_dpp v161, v161, v161 quad_perm:[2,3,0,1] row_mask:0xf bank_mask:0xf bound_ctrl:1
	v_add_f32_dpp v172, v172, v172 row_half_mirror row_mask:0xf bank_mask:0xf bound_ctrl:1
	v_add_f32_dpp v174, v174, v174 row_half_mirror row_mask:0xf bank_mask:0xf bound_ctrl:1
	v_add_f32_dpp v160, v160, v160 row_half_mirror row_mask:0xf bank_mask:0xf bound_ctrl:1
	v_add_f32_dpp v161, v161, v161 row_half_mirror row_mask:0xf bank_mask:0xf bound_ctrl:1
	s_waitcnt lgkmcnt(11)
	v_pk_fma_f32 v[72:73], v[192:193], v[172:173], v[218:219] op_sel_hi:[1,0,1]
	v_pk_fma_f32 v[80:81], v[192:193], v[174:175], v[226:227] op_sel_hi:[1,0,1]
	v_pk_fma_f32 v[74:75], v[194:195], v[172:173], v[220:221] op_sel_hi:[1,0,1]
	v_pk_fma_f32 v[82:83], v[194:195], v[174:175], v[228:229] op_sel_hi:[1,0,1]
	s_waitcnt lgkmcnt(10)
	v_pk_fma_f32 v[76:77], v[196:197], v[172:173], v[222:223] op_sel_hi:[1,0,1]
	v_pk_fma_f32 v[84:85], v[196:197], v[174:175], v[230:231] op_sel_hi:[1,0,1]
	v_pk_fma_f32 v[78:79], v[198:199], v[172:173], v[224:225] op_sel_hi:[1,0,1]
	v_pk_fma_f32 v[86:87], v[198:199], v[174:175], v[234:235] op_sel_hi:[1,0,1]
	ds_read_b128 v[192:195], v2 offset:8960
	ds_read_b128 v[196:199], v2 offset:8976
	ds_write_b64 v1, v[160:161] offset:54272
	s_waitcnt lgkmcnt(11)
	v_pk_mul_f32 v[164:165], v[72:73], v[176:177]
	v_pk_mul_f32 v[166:167], v[80:81], v[176:177]
	s_waitcnt lgkmcnt(9)
	v_pk_mul_f32 v[168:169], v[72:73], v[208:209]
	v_pk_mul_f32 v[170:171], v[80:81], v[208:209]
	v_pk_fma_f32 v[164:165], v[74:75], v[178:179], v[164:165]
	v_pk_fma_f32 v[166:167], v[82:83], v[178:179], v[166:167]
	v_pk_fma_f32 v[168:169], v[74:75], v[210:211], v[168:169]
	v_pk_fma_f32 v[170:171], v[82:83], v[210:211], v[170:171]
	v_pk_fma_f32 v[164:165], v[76:77], v[180:181], v[164:165]
	v_pk_fma_f32 v[166:167], v[84:85], v[180:181], v[166:167]
	s_waitcnt lgkmcnt(8)
	v_pk_fma_f32 v[168:169], v[76:77], v[212:213], v[168:169]
	v_pk_fma_f32 v[170:171], v[84:85], v[212:213], v[170:171]
	v_pk_fma_f32 v[164:165], v[78:79], v[182:183], v[164:165]
	v_pk_fma_f32 v[166:167], v[86:87], v[182:183], v[166:167]
	v_pk_fma_f32 v[168:169], v[78:79], v[214:215], v[168:169]
	v_pk_fma_f32 v[170:171], v[86:87], v[214:215], v[170:171]
	ds_read_b128 v[176:179], v2 offset:5120
	ds_read_b128 v[180:183], v2 offset:5136
	ds_read_b128 v[208:211], v2 offset:17152
	ds_read_b128 v[212:215], v2 offset:17168
	s_waitcnt lgkmcnt(9)
	v_pk_mul_f32 v[218:219], v[216:217], v[200:201] op_sel_hi:[0,1]
	v_pk_mul_f32 v[226:227], v[216:217], v[200:201] op_sel:[1,0]
	v_pk_mul_f32 v[220:221], v[216:217], v[202:203] op_sel_hi:[0,1]
	v_pk_mul_f32 v[228:229], v[216:217], v[202:203] op_sel:[1,0]
	v_pk_mul_f32 v[222:223], v[216:217], v[204:205] op_sel_hi:[0,1]
	v_pk_mul_f32 v[230:231], v[216:217], v[204:205] op_sel:[1,0]
	v_pk_mul_f32 v[224:225], v[216:217], v[206:207] op_sel_hi:[0,1]
	v_pk_mul_f32 v[234:235], v[216:217], v[206:207] op_sel:[1,0]
	ds_read_b128 v[200:203], v2 offset:13312
	ds_read_b128 v[204:207], v2 offset:13328
	ds_read_b64 v[216:217], v3 offset:41984
	v_add_f32_e32 v172, v164, v165
	v_add_f32_e32 v174, v166, v167
	v_add_f32_e32 v160, v168, v169
	v_add_f32_e32 v161, v170, v171
	s_waitcnt lgkmcnt(11)
	v_pk_fma_f32 v[218:219], v[72:73], v[184:185], v[218:219]
	v_pk_fma_f32 v[226:227], v[80:81], v[184:185], v[226:227]
	v_pk_fma_f32 v[220:221], v[74:75], v[186:187], v[220:221]
	v_pk_fma_f32 v[228:229], v[82:83], v[186:187], v[228:229]
	v_add_f32_dpp v172, v172, v172 quad_perm:[1,0,3,2] row_mask:0xf bank_mask:0xf bound_ctrl:1
	v_add_f32_dpp v174, v174, v174 quad_perm:[1,0,3,2] row_mask:0xf bank_mask:0xf bound_ctrl:1
	v_add_f32_dpp v160, v160, v160 quad_perm:[1,0,3,2] row_mask:0xf bank_mask:0xf bound_ctrl:1
	v_add_f32_dpp v161, v161, v161 quad_perm:[1,0,3,2] row_mask:0xf bank_mask:0xf bound_ctrl:1
	s_waitcnt lgkmcnt(10)
	v_pk_fma_f32 v[222:223], v[76:77], v[188:189], v[222:223]
	v_pk_fma_f32 v[230:231], v[84:85], v[188:189], v[230:231]
	v_pk_fma_f32 v[224:225], v[78:79], v[190:191], v[224:225]
	v_pk_fma_f32 v[234:235], v[86:87], v[190:191], v[234:235]
	ds_read_b128 v[184:187], v2 offset:1024
	ds_read_b128 v[188:191], v2 offset:1040
	v_add_f32_dpp v172, v172, v172 quad_perm:[2,3,0,1] row_mask:0xf bank_mask:0xf bound_ctrl:1
	v_add_f32_dpp v174, v174, v174 quad_perm:[2,3,0,1] row_mask:0xf bank_mask:0xf bound_ctrl:1
	v_add_f32_dpp v160, v160, v160 quad_perm:[2,3,0,1] row_mask:0xf bank_mask:0xf bound_ctrl:1
	v_add_f32_dpp v161, v161, v161 quad_perm:[2,3,0,1] row_mask:0xf bank_mask:0xf bound_ctrl:1
	v_add_f32_dpp v172, v172, v172 row_half_mirror row_mask:0xf bank_mask:0xf bound_ctrl:1
	v_add_f32_dpp v174, v174, v174 row_half_mirror row_mask:0xf bank_mask:0xf bound_ctrl:1
	v_add_f32_dpp v160, v160, v160 row_half_mirror row_mask:0xf bank_mask:0xf bound_ctrl:1
	v_add_f32_dpp v161, v161, v161 row_half_mirror row_mask:0xf bank_mask:0xf bound_ctrl:1
	s_waitcnt lgkmcnt(11)
	v_pk_fma_f32 v[72:73], v[192:193], v[172:173], v[218:219] op_sel_hi:[1,0,1]
	v_pk_fma_f32 v[80:81], v[192:193], v[174:175], v[226:227] op_sel_hi:[1,0,1]
	v_pk_fma_f32 v[74:75], v[194:195], v[172:173], v[220:221] op_sel_hi:[1,0,1]
	v_pk_fma_f32 v[82:83], v[194:195], v[174:175], v[228:229] op_sel_hi:[1,0,1]
	s_waitcnt lgkmcnt(10)
	v_pk_fma_f32 v[76:77], v[196:197], v[172:173], v[222:223] op_sel_hi:[1,0,1]
	v_pk_fma_f32 v[84:85], v[196:197], v[174:175], v[230:231] op_sel_hi:[1,0,1]
	v_pk_fma_f32 v[78:79], v[198:199], v[172:173], v[224:225] op_sel_hi:[1,0,1]
	v_pk_fma_f32 v[86:87], v[198:199], v[174:175], v[234:235] op_sel_hi:[1,0,1]
	ds_read_b128 v[192:195], v2 offset:9216
	ds_read_b128 v[196:199], v2 offset:9232
	ds_write_b64 v1, v[160:161] offset:54528
	s_waitcnt lgkmcnt(11)
	v_pk_mul_f32 v[164:165], v[72:73], v[176:177]
	v_pk_mul_f32 v[166:167], v[80:81], v[176:177]
	s_waitcnt lgkmcnt(9)
	v_pk_mul_f32 v[168:169], v[72:73], v[208:209]
	v_pk_mul_f32 v[170:171], v[80:81], v[208:209]
	v_pk_fma_f32 v[164:165], v[74:75], v[178:179], v[164:165]
	v_pk_fma_f32 v[166:167], v[82:83], v[178:179], v[166:167]
	v_pk_fma_f32 v[168:169], v[74:75], v[210:211], v[168:169]
	v_pk_fma_f32 v[170:171], v[82:83], v[210:211], v[170:171]
	v_pk_fma_f32 v[164:165], v[76:77], v[180:181], v[164:165]
	v_pk_fma_f32 v[166:167], v[84:85], v[180:181], v[166:167]
	s_waitcnt lgkmcnt(8)
	v_pk_fma_f32 v[168:169], v[76:77], v[212:213], v[168:169]
	v_pk_fma_f32 v[170:171], v[84:85], v[212:213], v[170:171]
	v_pk_fma_f32 v[164:165], v[78:79], v[182:183], v[164:165]
	v_pk_fma_f32 v[166:167], v[86:87], v[182:183], v[166:167]
	v_pk_fma_f32 v[168:169], v[78:79], v[214:215], v[168:169]
	v_pk_fma_f32 v[170:171], v[86:87], v[214:215], v[170:171]
	ds_read_b128 v[176:179], v2 offset:5376
	ds_read_b128 v[180:183], v2 offset:5392
	ds_read_b128 v[208:211], v2 offset:17408
	ds_read_b128 v[212:215], v2 offset:17424
	s_waitcnt lgkmcnt(9)
	v_pk_mul_f32 v[218:219], v[216:217], v[200:201] op_sel_hi:[0,1]
	v_pk_mul_f32 v[226:227], v[216:217], v[200:201] op_sel:[1,0]
	v_pk_mul_f32 v[220:221], v[216:217], v[202:203] op_sel_hi:[0,1]
	v_pk_mul_f32 v[228:229], v[216:217], v[202:203] op_sel:[1,0]
	v_pk_mul_f32 v[222:223], v[216:217], v[204:205] op_sel_hi:[0,1]
	v_pk_mul_f32 v[230:231], v[216:217], v[204:205] op_sel:[1,0]
	v_pk_mul_f32 v[224:225], v[216:217], v[206:207] op_sel_hi:[0,1]
	v_pk_mul_f32 v[234:235], v[216:217], v[206:207] op_sel:[1,0]
	ds_read_b128 v[200:203], v2 offset:13568
	ds_read_b128 v[204:207], v2 offset:13584
	ds_read_b64 v[216:217], v3 offset:42240
	v_add_f32_e32 v172, v164, v165
	v_add_f32_e32 v174, v166, v167
	v_add_f32_e32 v160, v168, v169
	v_add_f32_e32 v161, v170, v171
	s_waitcnt lgkmcnt(11)
	v_pk_fma_f32 v[218:219], v[72:73], v[184:185], v[218:219]
	v_pk_fma_f32 v[226:227], v[80:81], v[184:185], v[226:227]
	v_pk_fma_f32 v[220:221], v[74:75], v[186:187], v[220:221]
	v_pk_fma_f32 v[228:229], v[82:83], v[186:187], v[228:229]
	v_add_f32_dpp v172, v172, v172 quad_perm:[1,0,3,2] row_mask:0xf bank_mask:0xf bound_ctrl:1
	v_add_f32_dpp v174, v174, v174 quad_perm:[1,0,3,2] row_mask:0xf bank_mask:0xf bound_ctrl:1
	v_add_f32_dpp v160, v160, v160 quad_perm:[1,0,3,2] row_mask:0xf bank_mask:0xf bound_ctrl:1
	v_add_f32_dpp v161, v161, v161 quad_perm:[1,0,3,2] row_mask:0xf bank_mask:0xf bound_ctrl:1
	s_waitcnt lgkmcnt(10)
	v_pk_fma_f32 v[222:223], v[76:77], v[188:189], v[222:223]
	v_pk_fma_f32 v[230:231], v[84:85], v[188:189], v[230:231]
	v_pk_fma_f32 v[224:225], v[78:79], v[190:191], v[224:225]
	v_pk_fma_f32 v[234:235], v[86:87], v[190:191], v[234:235]
	ds_read_b128 v[184:187], v2 offset:1280
	ds_read_b128 v[188:191], v2 offset:1296
	v_add_f32_dpp v172, v172, v172 quad_perm:[2,3,0,1] row_mask:0xf bank_mask:0xf bound_ctrl:1
	v_add_f32_dpp v174, v174, v174 quad_perm:[2,3,0,1] row_mask:0xf bank_mask:0xf bound_ctrl:1
	v_add_f32_dpp v160, v160, v160 quad_perm:[2,3,0,1] row_mask:0xf bank_mask:0xf bound_ctrl:1
	v_add_f32_dpp v161, v161, v161 quad_perm:[2,3,0,1] row_mask:0xf bank_mask:0xf bound_ctrl:1
	v_add_f32_dpp v172, v172, v172 row_half_mirror row_mask:0xf bank_mask:0xf bound_ctrl:1
	v_add_f32_dpp v174, v174, v174 row_half_mirror row_mask:0xf bank_mask:0xf bound_ctrl:1
	v_add_f32_dpp v160, v160, v160 row_half_mirror row_mask:0xf bank_mask:0xf bound_ctrl:1
	v_add_f32_dpp v161, v161, v161 row_half_mirror row_mask:0xf bank_mask:0xf bound_ctrl:1
	s_waitcnt lgkmcnt(11)
	v_pk_fma_f32 v[72:73], v[192:193], v[172:173], v[218:219] op_sel_hi:[1,0,1]
	v_pk_fma_f32 v[80:81], v[192:193], v[174:175], v[226:227] op_sel_hi:[1,0,1]
	v_pk_fma_f32 v[74:75], v[194:195], v[172:173], v[220:221] op_sel_hi:[1,0,1]
	v_pk_fma_f32 v[82:83], v[194:195], v[174:175], v[228:229] op_sel_hi:[1,0,1]
	s_waitcnt lgkmcnt(10)
	v_pk_fma_f32 v[76:77], v[196:197], v[172:173], v[222:223] op_sel_hi:[1,0,1]
	v_pk_fma_f32 v[84:85], v[196:197], v[174:175], v[230:231] op_sel_hi:[1,0,1]
	v_pk_fma_f32 v[78:79], v[198:199], v[172:173], v[224:225] op_sel_hi:[1,0,1]
	v_pk_fma_f32 v[86:87], v[198:199], v[174:175], v[234:235] op_sel_hi:[1,0,1]
	ds_read_b128 v[192:195], v2 offset:9472
	ds_read_b128 v[196:199], v2 offset:9488
	ds_write_b64 v1, v[160:161] offset:54784
	s_waitcnt lgkmcnt(11)
	v_pk_mul_f32 v[164:165], v[72:73], v[176:177]
	v_pk_mul_f32 v[166:167], v[80:81], v[176:177]
	s_waitcnt lgkmcnt(9)
	v_pk_mul_f32 v[168:169], v[72:73], v[208:209]
	v_pk_mul_f32 v[170:171], v[80:81], v[208:209]
	v_pk_fma_f32 v[164:165], v[74:75], v[178:179], v[164:165]
	v_pk_fma_f32 v[166:167], v[82:83], v[178:179], v[166:167]
	v_pk_fma_f32 v[168:169], v[74:75], v[210:211], v[168:169]
	v_pk_fma_f32 v[170:171], v[82:83], v[210:211], v[170:171]
	v_pk_fma_f32 v[164:165], v[76:77], v[180:181], v[164:165]
	v_pk_fma_f32 v[166:167], v[84:85], v[180:181], v[166:167]
	s_waitcnt lgkmcnt(8)
	v_pk_fma_f32 v[168:169], v[76:77], v[212:213], v[168:169]
	v_pk_fma_f32 v[170:171], v[84:85], v[212:213], v[170:171]
	v_pk_fma_f32 v[164:165], v[78:79], v[182:183], v[164:165]
	v_pk_fma_f32 v[166:167], v[86:87], v[182:183], v[166:167]
	v_pk_fma_f32 v[168:169], v[78:79], v[214:215], v[168:169]
	v_pk_fma_f32 v[170:171], v[86:87], v[214:215], v[170:171]
	ds_read_b128 v[176:179], v2 offset:5632
	ds_read_b128 v[180:183], v2 offset:5648
	ds_read_b128 v[208:211], v2 offset:17664
	ds_read_b128 v[212:215], v2 offset:17680
	s_waitcnt lgkmcnt(9)
	v_pk_mul_f32 v[218:219], v[216:217], v[200:201] op_sel_hi:[0,1]
	v_pk_mul_f32 v[226:227], v[216:217], v[200:201] op_sel:[1,0]
	v_pk_mul_f32 v[220:221], v[216:217], v[202:203] op_sel_hi:[0,1]
	v_pk_mul_f32 v[228:229], v[216:217], v[202:203] op_sel:[1,0]
	v_pk_mul_f32 v[222:223], v[216:217], v[204:205] op_sel_hi:[0,1]
	v_pk_mul_f32 v[230:231], v[216:217], v[204:205] op_sel:[1,0]
	v_pk_mul_f32 v[224:225], v[216:217], v[206:207] op_sel_hi:[0,1]
	v_pk_mul_f32 v[234:235], v[216:217], v[206:207] op_sel:[1,0]
	ds_read_b128 v[200:203], v2 offset:13824
	ds_read_b128 v[204:207], v2 offset:13840
	ds_read_b64 v[216:217], v3 offset:42496
	v_add_f32_e32 v172, v164, v165
	v_add_f32_e32 v174, v166, v167
	v_add_f32_e32 v160, v168, v169
	v_add_f32_e32 v161, v170, v171
	s_waitcnt lgkmcnt(11)
	v_pk_fma_f32 v[218:219], v[72:73], v[184:185], v[218:219]
	v_pk_fma_f32 v[226:227], v[80:81], v[184:185], v[226:227]
	v_pk_fma_f32 v[220:221], v[74:75], v[186:187], v[220:221]
	v_pk_fma_f32 v[228:229], v[82:83], v[186:187], v[228:229]
	v_add_f32_dpp v172, v172, v172 quad_perm:[1,0,3,2] row_mask:0xf bank_mask:0xf bound_ctrl:1
	v_add_f32_dpp v174, v174, v174 quad_perm:[1,0,3,2] row_mask:0xf bank_mask:0xf bound_ctrl:1
	v_add_f32_dpp v160, v160, v160 quad_perm:[1,0,3,2] row_mask:0xf bank_mask:0xf bound_ctrl:1
	v_add_f32_dpp v161, v161, v161 quad_perm:[1,0,3,2] row_mask:0xf bank_mask:0xf bound_ctrl:1
	s_waitcnt lgkmcnt(10)
	v_pk_fma_f32 v[222:223], v[76:77], v[188:189], v[222:223]
	v_pk_fma_f32 v[230:231], v[84:85], v[188:189], v[230:231]
	v_pk_fma_f32 v[224:225], v[78:79], v[190:191], v[224:225]
	v_pk_fma_f32 v[234:235], v[86:87], v[190:191], v[234:235]
	ds_read_b128 v[184:187], v2 offset:1536
	ds_read_b128 v[188:191], v2 offset:1552
	v_add_f32_dpp v172, v172, v172 quad_perm:[2,3,0,1] row_mask:0xf bank_mask:0xf bound_ctrl:1
	v_add_f32_dpp v174, v174, v174 quad_perm:[2,3,0,1] row_mask:0xf bank_mask:0xf bound_ctrl:1
	v_add_f32_dpp v160, v160, v160 quad_perm:[2,3,0,1] row_mask:0xf bank_mask:0xf bound_ctrl:1
	v_add_f32_dpp v161, v161, v161 quad_perm:[2,3,0,1] row_mask:0xf bank_mask:0xf bound_ctrl:1
	v_add_f32_dpp v172, v172, v172 row_half_mirror row_mask:0xf bank_mask:0xf bound_ctrl:1
	v_add_f32_dpp v174, v174, v174 row_half_mirror row_mask:0xf bank_mask:0xf bound_ctrl:1
	v_add_f32_dpp v160, v160, v160 row_half_mirror row_mask:0xf bank_mask:0xf bound_ctrl:1
	v_add_f32_dpp v161, v161, v161 row_half_mirror row_mask:0xf bank_mask:0xf bound_ctrl:1
	s_waitcnt lgkmcnt(11)
	v_pk_fma_f32 v[72:73], v[192:193], v[172:173], v[218:219] op_sel_hi:[1,0,1]
	v_pk_fma_f32 v[80:81], v[192:193], v[174:175], v[226:227] op_sel_hi:[1,0,1]
	v_pk_fma_f32 v[74:75], v[194:195], v[172:173], v[220:221] op_sel_hi:[1,0,1]
	v_pk_fma_f32 v[82:83], v[194:195], v[174:175], v[228:229] op_sel_hi:[1,0,1]
	s_waitcnt lgkmcnt(10)
	v_pk_fma_f32 v[76:77], v[196:197], v[172:173], v[222:223] op_sel_hi:[1,0,1]
	v_pk_fma_f32 v[84:85], v[196:197], v[174:175], v[230:231] op_sel_hi:[1,0,1]
	v_pk_fma_f32 v[78:79], v[198:199], v[172:173], v[224:225] op_sel_hi:[1,0,1]
	v_pk_fma_f32 v[86:87], v[198:199], v[174:175], v[234:235] op_sel_hi:[1,0,1]
	ds_read_b128 v[192:195], v2 offset:9728
	ds_read_b128 v[196:199], v2 offset:9744
	ds_write_b64 v1, v[160:161] offset:55040
	s_waitcnt lgkmcnt(11)
	v_pk_mul_f32 v[164:165], v[72:73], v[176:177]
	v_pk_mul_f32 v[166:167], v[80:81], v[176:177]
	s_waitcnt lgkmcnt(9)
	v_pk_mul_f32 v[168:169], v[72:73], v[208:209]
	v_pk_mul_f32 v[170:171], v[80:81], v[208:209]
	v_pk_fma_f32 v[164:165], v[74:75], v[178:179], v[164:165]
	v_pk_fma_f32 v[166:167], v[82:83], v[178:179], v[166:167]
	v_pk_fma_f32 v[168:169], v[74:75], v[210:211], v[168:169]
	v_pk_fma_f32 v[170:171], v[82:83], v[210:211], v[170:171]
	v_pk_fma_f32 v[164:165], v[76:77], v[180:181], v[164:165]
	v_pk_fma_f32 v[166:167], v[84:85], v[180:181], v[166:167]
	s_waitcnt lgkmcnt(8)
	v_pk_fma_f32 v[168:169], v[76:77], v[212:213], v[168:169]
	v_pk_fma_f32 v[170:171], v[84:85], v[212:213], v[170:171]
	v_pk_fma_f32 v[164:165], v[78:79], v[182:183], v[164:165]
	v_pk_fma_f32 v[166:167], v[86:87], v[182:183], v[166:167]
	v_pk_fma_f32 v[168:169], v[78:79], v[214:215], v[168:169]
	v_pk_fma_f32 v[170:171], v[86:87], v[214:215], v[170:171]
	ds_read_b128 v[176:179], v2 offset:5888
	ds_read_b128 v[180:183], v2 offset:5904
	ds_read_b128 v[208:211], v2 offset:17920
	ds_read_b128 v[212:215], v2 offset:17936
	s_waitcnt lgkmcnt(9)
	v_pk_mul_f32 v[218:219], v[216:217], v[200:201] op_sel_hi:[0,1]
	v_pk_mul_f32 v[226:227], v[216:217], v[200:201] op_sel:[1,0]
	v_pk_mul_f32 v[220:221], v[216:217], v[202:203] op_sel_hi:[0,1]
	v_pk_mul_f32 v[228:229], v[216:217], v[202:203] op_sel:[1,0]
	v_pk_mul_f32 v[222:223], v[216:217], v[204:205] op_sel_hi:[0,1]
	v_pk_mul_f32 v[230:231], v[216:217], v[204:205] op_sel:[1,0]
	v_pk_mul_f32 v[224:225], v[216:217], v[206:207] op_sel_hi:[0,1]
	v_pk_mul_f32 v[234:235], v[216:217], v[206:207] op_sel:[1,0]
	ds_read_b128 v[200:203], v2 offset:14080
	ds_read_b128 v[204:207], v2 offset:14096
	ds_read_b64 v[216:217], v3 offset:42752
	v_add_f32_e32 v172, v164, v165
	v_add_f32_e32 v174, v166, v167
	v_add_f32_e32 v160, v168, v169
	v_add_f32_e32 v161, v170, v171
	s_waitcnt lgkmcnt(11)
	v_pk_fma_f32 v[218:219], v[72:73], v[184:185], v[218:219]
	v_pk_fma_f32 v[226:227], v[80:81], v[184:185], v[226:227]
	v_pk_fma_f32 v[220:221], v[74:75], v[186:187], v[220:221]
	v_pk_fma_f32 v[228:229], v[82:83], v[186:187], v[228:229]
	v_add_f32_dpp v172, v172, v172 quad_perm:[1,0,3,2] row_mask:0xf bank_mask:0xf bound_ctrl:1
	v_add_f32_dpp v174, v174, v174 quad_perm:[1,0,3,2] row_mask:0xf bank_mask:0xf bound_ctrl:1
	v_add_f32_dpp v160, v160, v160 quad_perm:[1,0,3,2] row_mask:0xf bank_mask:0xf bound_ctrl:1
	v_add_f32_dpp v161, v161, v161 quad_perm:[1,0,3,2] row_mask:0xf bank_mask:0xf bound_ctrl:1
	s_waitcnt lgkmcnt(10)
	v_pk_fma_f32 v[222:223], v[76:77], v[188:189], v[222:223]
	v_pk_fma_f32 v[230:231], v[84:85], v[188:189], v[230:231]
	v_pk_fma_f32 v[224:225], v[78:79], v[190:191], v[224:225]
	v_pk_fma_f32 v[234:235], v[86:87], v[190:191], v[234:235]
	ds_read_b128 v[184:187], v2 offset:1792
	ds_read_b128 v[188:191], v2 offset:1808
	v_add_f32_dpp v172, v172, v172 quad_perm:[2,3,0,1] row_mask:0xf bank_mask:0xf bound_ctrl:1
	v_add_f32_dpp v174, v174, v174 quad_perm:[2,3,0,1] row_mask:0xf bank_mask:0xf bound_ctrl:1
	v_add_f32_dpp v160, v160, v160 quad_perm:[2,3,0,1] row_mask:0xf bank_mask:0xf bound_ctrl:1
	v_add_f32_dpp v161, v161, v161 quad_perm:[2,3,0,1] row_mask:0xf bank_mask:0xf bound_ctrl:1
	v_add_f32_dpp v172, v172, v172 row_half_mirror row_mask:0xf bank_mask:0xf bound_ctrl:1
	v_add_f32_dpp v174, v174, v174 row_half_mirror row_mask:0xf bank_mask:0xf bound_ctrl:1
	v_add_f32_dpp v160, v160, v160 row_half_mirror row_mask:0xf bank_mask:0xf bound_ctrl:1
	v_add_f32_dpp v161, v161, v161 row_half_mirror row_mask:0xf bank_mask:0xf bound_ctrl:1
	s_waitcnt lgkmcnt(11)
	v_pk_fma_f32 v[72:73], v[192:193], v[172:173], v[218:219] op_sel_hi:[1,0,1]
	v_pk_fma_f32 v[80:81], v[192:193], v[174:175], v[226:227] op_sel_hi:[1,0,1]
	v_pk_fma_f32 v[74:75], v[194:195], v[172:173], v[220:221] op_sel_hi:[1,0,1]
	v_pk_fma_f32 v[82:83], v[194:195], v[174:175], v[228:229] op_sel_hi:[1,0,1]
	s_waitcnt lgkmcnt(10)
	v_pk_fma_f32 v[76:77], v[196:197], v[172:173], v[222:223] op_sel_hi:[1,0,1]
	v_pk_fma_f32 v[84:85], v[196:197], v[174:175], v[230:231] op_sel_hi:[1,0,1]
	v_pk_fma_f32 v[78:79], v[198:199], v[172:173], v[224:225] op_sel_hi:[1,0,1]
	v_pk_fma_f32 v[86:87], v[198:199], v[174:175], v[234:235] op_sel_hi:[1,0,1]
	ds_read_b128 v[192:195], v2 offset:9984
	ds_read_b128 v[196:199], v2 offset:10000
	ds_write_b64 v1, v[160:161] offset:55296
	s_waitcnt lgkmcnt(11)
	v_pk_mul_f32 v[164:165], v[72:73], v[176:177]
	v_pk_mul_f32 v[166:167], v[80:81], v[176:177]
	s_waitcnt lgkmcnt(9)
	v_pk_mul_f32 v[168:169], v[72:73], v[208:209]
	v_pk_mul_f32 v[170:171], v[80:81], v[208:209]
	v_pk_fma_f32 v[164:165], v[74:75], v[178:179], v[164:165]
	v_pk_fma_f32 v[166:167], v[82:83], v[178:179], v[166:167]
	v_pk_fma_f32 v[168:169], v[74:75], v[210:211], v[168:169]
	v_pk_fma_f32 v[170:171], v[82:83], v[210:211], v[170:171]
	v_pk_fma_f32 v[164:165], v[76:77], v[180:181], v[164:165]
	v_pk_fma_f32 v[166:167], v[84:85], v[180:181], v[166:167]
	s_waitcnt lgkmcnt(8)
	v_pk_fma_f32 v[168:169], v[76:77], v[212:213], v[168:169]
	v_pk_fma_f32 v[170:171], v[84:85], v[212:213], v[170:171]
	v_pk_fma_f32 v[164:165], v[78:79], v[182:183], v[164:165]
	v_pk_fma_f32 v[166:167], v[86:87], v[182:183], v[166:167]
	v_pk_fma_f32 v[168:169], v[78:79], v[214:215], v[168:169]
	v_pk_fma_f32 v[170:171], v[86:87], v[214:215], v[170:171]
	ds_read_b128 v[176:179], v2 offset:6144
	ds_read_b128 v[180:183], v2 offset:6160
	ds_read_b128 v[208:211], v2 offset:18176
	ds_read_b128 v[212:215], v2 offset:18192
	s_waitcnt lgkmcnt(9)
	v_pk_mul_f32 v[218:219], v[216:217], v[200:201] op_sel_hi:[0,1]
	v_pk_mul_f32 v[226:227], v[216:217], v[200:201] op_sel:[1,0]
	v_pk_mul_f32 v[220:221], v[216:217], v[202:203] op_sel_hi:[0,1]
	v_pk_mul_f32 v[228:229], v[216:217], v[202:203] op_sel:[1,0]
	v_pk_mul_f32 v[222:223], v[216:217], v[204:205] op_sel_hi:[0,1]
	v_pk_mul_f32 v[230:231], v[216:217], v[204:205] op_sel:[1,0]
	v_pk_mul_f32 v[224:225], v[216:217], v[206:207] op_sel_hi:[0,1]
	v_pk_mul_f32 v[234:235], v[216:217], v[206:207] op_sel:[1,0]
	ds_read_b128 v[200:203], v2 offset:14336
	ds_read_b128 v[204:207], v2 offset:14352
	ds_read_b64 v[216:217], v3 offset:43008
	v_add_f32_e32 v172, v164, v165
	v_add_f32_e32 v174, v166, v167
	v_add_f32_e32 v160, v168, v169
	v_add_f32_e32 v161, v170, v171
	s_waitcnt lgkmcnt(11)
	v_pk_fma_f32 v[218:219], v[72:73], v[184:185], v[218:219]
	v_pk_fma_f32 v[226:227], v[80:81], v[184:185], v[226:227]
	v_pk_fma_f32 v[220:221], v[74:75], v[186:187], v[220:221]
	v_pk_fma_f32 v[228:229], v[82:83], v[186:187], v[228:229]
	v_add_f32_dpp v172, v172, v172 quad_perm:[1,0,3,2] row_mask:0xf bank_mask:0xf bound_ctrl:1
	v_add_f32_dpp v174, v174, v174 quad_perm:[1,0,3,2] row_mask:0xf bank_mask:0xf bound_ctrl:1
	v_add_f32_dpp v160, v160, v160 quad_perm:[1,0,3,2] row_mask:0xf bank_mask:0xf bound_ctrl:1
	v_add_f32_dpp v161, v161, v161 quad_perm:[1,0,3,2] row_mask:0xf bank_mask:0xf bound_ctrl:1
	s_waitcnt lgkmcnt(10)
	v_pk_fma_f32 v[222:223], v[76:77], v[188:189], v[222:223]
	v_pk_fma_f32 v[230:231], v[84:85], v[188:189], v[230:231]
	v_pk_fma_f32 v[224:225], v[78:79], v[190:191], v[224:225]
	v_pk_fma_f32 v[234:235], v[86:87], v[190:191], v[234:235]
	ds_read_b128 v[184:187], v2 offset:2048
	ds_read_b128 v[188:191], v2 offset:2064
	v_add_f32_dpp v172, v172, v172 quad_perm:[2,3,0,1] row_mask:0xf bank_mask:0xf bound_ctrl:1
	v_add_f32_dpp v174, v174, v174 quad_perm:[2,3,0,1] row_mask:0xf bank_mask:0xf bound_ctrl:1
	v_add_f32_dpp v160, v160, v160 quad_perm:[2,3,0,1] row_mask:0xf bank_mask:0xf bound_ctrl:1
	v_add_f32_dpp v161, v161, v161 quad_perm:[2,3,0,1] row_mask:0xf bank_mask:0xf bound_ctrl:1
	v_add_f32_dpp v172, v172, v172 row_half_mirror row_mask:0xf bank_mask:0xf bound_ctrl:1
	v_add_f32_dpp v174, v174, v174 row_half_mirror row_mask:0xf bank_mask:0xf bound_ctrl:1
	v_add_f32_dpp v160, v160, v160 row_half_mirror row_mask:0xf bank_mask:0xf bound_ctrl:1
	v_add_f32_dpp v161, v161, v161 row_half_mirror row_mask:0xf bank_mask:0xf bound_ctrl:1
	s_waitcnt lgkmcnt(11)
	v_pk_fma_f32 v[72:73], v[192:193], v[172:173], v[218:219] op_sel_hi:[1,0,1]
	v_pk_fma_f32 v[80:81], v[192:193], v[174:175], v[226:227] op_sel_hi:[1,0,1]
	v_pk_fma_f32 v[74:75], v[194:195], v[172:173], v[220:221] op_sel_hi:[1,0,1]
	v_pk_fma_f32 v[82:83], v[194:195], v[174:175], v[228:229] op_sel_hi:[1,0,1]
	s_waitcnt lgkmcnt(10)
	v_pk_fma_f32 v[76:77], v[196:197], v[172:173], v[222:223] op_sel_hi:[1,0,1]
	v_pk_fma_f32 v[84:85], v[196:197], v[174:175], v[230:231] op_sel_hi:[1,0,1]
	v_pk_fma_f32 v[78:79], v[198:199], v[172:173], v[224:225] op_sel_hi:[1,0,1]
	v_pk_fma_f32 v[86:87], v[198:199], v[174:175], v[234:235] op_sel_hi:[1,0,1]
	ds_read_b128 v[192:195], v2 offset:10240
	ds_read_b128 v[196:199], v2 offset:10256
	ds_write_b64 v1, v[160:161] offset:55552
	s_waitcnt lgkmcnt(11)
	v_pk_mul_f32 v[164:165], v[72:73], v[176:177]
	v_pk_mul_f32 v[166:167], v[80:81], v[176:177]
	s_waitcnt lgkmcnt(9)
	v_pk_mul_f32 v[168:169], v[72:73], v[208:209]
	v_pk_mul_f32 v[170:171], v[80:81], v[208:209]
	v_pk_fma_f32 v[164:165], v[74:75], v[178:179], v[164:165]
	v_pk_fma_f32 v[166:167], v[82:83], v[178:179], v[166:167]
	v_pk_fma_f32 v[168:169], v[74:75], v[210:211], v[168:169]
	v_pk_fma_f32 v[170:171], v[82:83], v[210:211], v[170:171]
	v_pk_fma_f32 v[164:165], v[76:77], v[180:181], v[164:165]
	v_pk_fma_f32 v[166:167], v[84:85], v[180:181], v[166:167]
	s_waitcnt lgkmcnt(8)
	v_pk_fma_f32 v[168:169], v[76:77], v[212:213], v[168:169]
	v_pk_fma_f32 v[170:171], v[84:85], v[212:213], v[170:171]
	v_pk_fma_f32 v[164:165], v[78:79], v[182:183], v[164:165]
	v_pk_fma_f32 v[166:167], v[86:87], v[182:183], v[166:167]
	v_pk_fma_f32 v[168:169], v[78:79], v[214:215], v[168:169]
	v_pk_fma_f32 v[170:171], v[86:87], v[214:215], v[170:171]
	ds_read_b128 v[176:179], v2 offset:6400
	ds_read_b128 v[180:183], v2 offset:6416
	ds_read_b128 v[208:211], v2 offset:18432
	ds_read_b128 v[212:215], v2 offset:18448
	s_waitcnt lgkmcnt(9)
	v_pk_mul_f32 v[218:219], v[216:217], v[200:201] op_sel_hi:[0,1]
	v_pk_mul_f32 v[226:227], v[216:217], v[200:201] op_sel:[1,0]
	v_pk_mul_f32 v[220:221], v[216:217], v[202:203] op_sel_hi:[0,1]
	v_pk_mul_f32 v[228:229], v[216:217], v[202:203] op_sel:[1,0]
	v_pk_mul_f32 v[222:223], v[216:217], v[204:205] op_sel_hi:[0,1]
	v_pk_mul_f32 v[230:231], v[216:217], v[204:205] op_sel:[1,0]
	v_pk_mul_f32 v[224:225], v[216:217], v[206:207] op_sel_hi:[0,1]
	v_pk_mul_f32 v[234:235], v[216:217], v[206:207] op_sel:[1,0]
	ds_read_b128 v[200:203], v2 offset:14592
	ds_read_b128 v[204:207], v2 offset:14608
	ds_read_b64 v[216:217], v3 offset:43264
	v_add_f32_e32 v172, v164, v165
	v_add_f32_e32 v174, v166, v167
	v_add_f32_e32 v160, v168, v169
	v_add_f32_e32 v161, v170, v171
	s_waitcnt lgkmcnt(11)
	v_pk_fma_f32 v[218:219], v[72:73], v[184:185], v[218:219]
	v_pk_fma_f32 v[226:227], v[80:81], v[184:185], v[226:227]
	v_pk_fma_f32 v[220:221], v[74:75], v[186:187], v[220:221]
	v_pk_fma_f32 v[228:229], v[82:83], v[186:187], v[228:229]
	v_add_f32_dpp v172, v172, v172 quad_perm:[1,0,3,2] row_mask:0xf bank_mask:0xf bound_ctrl:1
	v_add_f32_dpp v174, v174, v174 quad_perm:[1,0,3,2] row_mask:0xf bank_mask:0xf bound_ctrl:1
	v_add_f32_dpp v160, v160, v160 quad_perm:[1,0,3,2] row_mask:0xf bank_mask:0xf bound_ctrl:1
	v_add_f32_dpp v161, v161, v161 quad_perm:[1,0,3,2] row_mask:0xf bank_mask:0xf bound_ctrl:1
	s_waitcnt lgkmcnt(10)
	v_pk_fma_f32 v[222:223], v[76:77], v[188:189], v[222:223]
	v_pk_fma_f32 v[230:231], v[84:85], v[188:189], v[230:231]
	v_pk_fma_f32 v[224:225], v[78:79], v[190:191], v[224:225]
	v_pk_fma_f32 v[234:235], v[86:87], v[190:191], v[234:235]
	ds_read_b128 v[184:187], v2 offset:2304
	ds_read_b128 v[188:191], v2 offset:2320
	v_add_f32_dpp v172, v172, v172 quad_perm:[2,3,0,1] row_mask:0xf bank_mask:0xf bound_ctrl:1
	v_add_f32_dpp v174, v174, v174 quad_perm:[2,3,0,1] row_mask:0xf bank_mask:0xf bound_ctrl:1
	v_add_f32_dpp v160, v160, v160 quad_perm:[2,3,0,1] row_mask:0xf bank_mask:0xf bound_ctrl:1
	v_add_f32_dpp v161, v161, v161 quad_perm:[2,3,0,1] row_mask:0xf bank_mask:0xf bound_ctrl:1
	v_add_f32_dpp v172, v172, v172 row_half_mirror row_mask:0xf bank_mask:0xf bound_ctrl:1
	v_add_f32_dpp v174, v174, v174 row_half_mirror row_mask:0xf bank_mask:0xf bound_ctrl:1
	v_add_f32_dpp v160, v160, v160 row_half_mirror row_mask:0xf bank_mask:0xf bound_ctrl:1
	v_add_f32_dpp v161, v161, v161 row_half_mirror row_mask:0xf bank_mask:0xf bound_ctrl:1
	s_waitcnt lgkmcnt(11)
	v_pk_fma_f32 v[72:73], v[192:193], v[172:173], v[218:219] op_sel_hi:[1,0,1]
	v_pk_fma_f32 v[80:81], v[192:193], v[174:175], v[226:227] op_sel_hi:[1,0,1]
	v_pk_fma_f32 v[74:75], v[194:195], v[172:173], v[220:221] op_sel_hi:[1,0,1]
	v_pk_fma_f32 v[82:83], v[194:195], v[174:175], v[228:229] op_sel_hi:[1,0,1]
	s_waitcnt lgkmcnt(10)
	v_pk_fma_f32 v[76:77], v[196:197], v[172:173], v[222:223] op_sel_hi:[1,0,1]
	v_pk_fma_f32 v[84:85], v[196:197], v[174:175], v[230:231] op_sel_hi:[1,0,1]
	v_pk_fma_f32 v[78:79], v[198:199], v[172:173], v[224:225] op_sel_hi:[1,0,1]
	v_pk_fma_f32 v[86:87], v[198:199], v[174:175], v[234:235] op_sel_hi:[1,0,1]
	ds_read_b128 v[192:195], v2 offset:10496
	ds_read_b128 v[196:199], v2 offset:10512
	ds_write_b64 v1, v[160:161] offset:55808
	s_waitcnt lgkmcnt(11)
	v_pk_mul_f32 v[164:165], v[72:73], v[176:177]
	v_pk_mul_f32 v[166:167], v[80:81], v[176:177]
	s_waitcnt lgkmcnt(9)
	v_pk_mul_f32 v[168:169], v[72:73], v[208:209]
	v_pk_mul_f32 v[170:171], v[80:81], v[208:209]
	v_pk_fma_f32 v[164:165], v[74:75], v[178:179], v[164:165]
	v_pk_fma_f32 v[166:167], v[82:83], v[178:179], v[166:167]
	v_pk_fma_f32 v[168:169], v[74:75], v[210:211], v[168:169]
	v_pk_fma_f32 v[170:171], v[82:83], v[210:211], v[170:171]
	v_pk_fma_f32 v[164:165], v[76:77], v[180:181], v[164:165]
	v_pk_fma_f32 v[166:167], v[84:85], v[180:181], v[166:167]
	s_waitcnt lgkmcnt(8)
	v_pk_fma_f32 v[168:169], v[76:77], v[212:213], v[168:169]
	v_pk_fma_f32 v[170:171], v[84:85], v[212:213], v[170:171]
	v_pk_fma_f32 v[164:165], v[78:79], v[182:183], v[164:165]
	v_pk_fma_f32 v[166:167], v[86:87], v[182:183], v[166:167]
	v_pk_fma_f32 v[168:169], v[78:79], v[214:215], v[168:169]
	v_pk_fma_f32 v[170:171], v[86:87], v[214:215], v[170:171]
	ds_read_b128 v[176:179], v2 offset:6656
	ds_read_b128 v[180:183], v2 offset:6672
	ds_read_b128 v[208:211], v2 offset:18688
	ds_read_b128 v[212:215], v2 offset:18704
	s_waitcnt lgkmcnt(9)
	v_pk_mul_f32 v[218:219], v[216:217], v[200:201] op_sel_hi:[0,1]
	v_pk_mul_f32 v[226:227], v[216:217], v[200:201] op_sel:[1,0]
	v_pk_mul_f32 v[220:221], v[216:217], v[202:203] op_sel_hi:[0,1]
	v_pk_mul_f32 v[228:229], v[216:217], v[202:203] op_sel:[1,0]
	v_pk_mul_f32 v[222:223], v[216:217], v[204:205] op_sel_hi:[0,1]
	v_pk_mul_f32 v[230:231], v[216:217], v[204:205] op_sel:[1,0]
	v_pk_mul_f32 v[224:225], v[216:217], v[206:207] op_sel_hi:[0,1]
	v_pk_mul_f32 v[234:235], v[216:217], v[206:207] op_sel:[1,0]
	ds_read_b128 v[200:203], v2 offset:14848
	ds_read_b128 v[204:207], v2 offset:14864
	ds_read_b64 v[216:217], v3 offset:43520
	v_add_f32_e32 v172, v164, v165
	v_add_f32_e32 v174, v166, v167
	v_add_f32_e32 v160, v168, v169
	v_add_f32_e32 v161, v170, v171
	s_waitcnt lgkmcnt(11)
	v_pk_fma_f32 v[218:219], v[72:73], v[184:185], v[218:219]
	v_pk_fma_f32 v[226:227], v[80:81], v[184:185], v[226:227]
	v_pk_fma_f32 v[220:221], v[74:75], v[186:187], v[220:221]
	v_pk_fma_f32 v[228:229], v[82:83], v[186:187], v[228:229]
	v_add_f32_dpp v172, v172, v172 quad_perm:[1,0,3,2] row_mask:0xf bank_mask:0xf bound_ctrl:1
	v_add_f32_dpp v174, v174, v174 quad_perm:[1,0,3,2] row_mask:0xf bank_mask:0xf bound_ctrl:1
	v_add_f32_dpp v160, v160, v160 quad_perm:[1,0,3,2] row_mask:0xf bank_mask:0xf bound_ctrl:1
	v_add_f32_dpp v161, v161, v161 quad_perm:[1,0,3,2] row_mask:0xf bank_mask:0xf bound_ctrl:1
	s_waitcnt lgkmcnt(10)
	v_pk_fma_f32 v[222:223], v[76:77], v[188:189], v[222:223]
	v_pk_fma_f32 v[230:231], v[84:85], v[188:189], v[230:231]
	v_pk_fma_f32 v[224:225], v[78:79], v[190:191], v[224:225]
	v_pk_fma_f32 v[234:235], v[86:87], v[190:191], v[234:235]
	ds_read_b128 v[184:187], v2 offset:2560
	ds_read_b128 v[188:191], v2 offset:2576
	v_add_f32_dpp v172, v172, v172 quad_perm:[2,3,0,1] row_mask:0xf bank_mask:0xf bound_ctrl:1
	v_add_f32_dpp v174, v174, v174 quad_perm:[2,3,0,1] row_mask:0xf bank_mask:0xf bound_ctrl:1
	v_add_f32_dpp v160, v160, v160 quad_perm:[2,3,0,1] row_mask:0xf bank_mask:0xf bound_ctrl:1
	v_add_f32_dpp v161, v161, v161 quad_perm:[2,3,0,1] row_mask:0xf bank_mask:0xf bound_ctrl:1
	v_add_f32_dpp v172, v172, v172 row_half_mirror row_mask:0xf bank_mask:0xf bound_ctrl:1
	v_add_f32_dpp v174, v174, v174 row_half_mirror row_mask:0xf bank_mask:0xf bound_ctrl:1
	v_add_f32_dpp v160, v160, v160 row_half_mirror row_mask:0xf bank_mask:0xf bound_ctrl:1
	v_add_f32_dpp v161, v161, v161 row_half_mirror row_mask:0xf bank_mask:0xf bound_ctrl:1
	s_waitcnt lgkmcnt(11)
	v_pk_fma_f32 v[72:73], v[192:193], v[172:173], v[218:219] op_sel_hi:[1,0,1]
	v_pk_fma_f32 v[80:81], v[192:193], v[174:175], v[226:227] op_sel_hi:[1,0,1]
	v_pk_fma_f32 v[74:75], v[194:195], v[172:173], v[220:221] op_sel_hi:[1,0,1]
	v_pk_fma_f32 v[82:83], v[194:195], v[174:175], v[228:229] op_sel_hi:[1,0,1]
	s_waitcnt lgkmcnt(10)
	v_pk_fma_f32 v[76:77], v[196:197], v[172:173], v[222:223] op_sel_hi:[1,0,1]
	v_pk_fma_f32 v[84:85], v[196:197], v[174:175], v[230:231] op_sel_hi:[1,0,1]
	v_pk_fma_f32 v[78:79], v[198:199], v[172:173], v[224:225] op_sel_hi:[1,0,1]
	v_pk_fma_f32 v[86:87], v[198:199], v[174:175], v[234:235] op_sel_hi:[1,0,1]
	ds_read_b128 v[192:195], v2 offset:10752
	ds_read_b128 v[196:199], v2 offset:10768
	ds_write_b64 v1, v[160:161] offset:56064
	s_waitcnt lgkmcnt(11)
	v_pk_mul_f32 v[164:165], v[72:73], v[176:177]
	v_pk_mul_f32 v[166:167], v[80:81], v[176:177]
	s_waitcnt lgkmcnt(9)
	v_pk_mul_f32 v[168:169], v[72:73], v[208:209]
	v_pk_mul_f32 v[170:171], v[80:81], v[208:209]
	v_pk_fma_f32 v[164:165], v[74:75], v[178:179], v[164:165]
	v_pk_fma_f32 v[166:167], v[82:83], v[178:179], v[166:167]
	v_pk_fma_f32 v[168:169], v[74:75], v[210:211], v[168:169]
	v_pk_fma_f32 v[170:171], v[82:83], v[210:211], v[170:171]
	v_pk_fma_f32 v[164:165], v[76:77], v[180:181], v[164:165]
	v_pk_fma_f32 v[166:167], v[84:85], v[180:181], v[166:167]
	s_waitcnt lgkmcnt(8)
	v_pk_fma_f32 v[168:169], v[76:77], v[212:213], v[168:169]
	v_pk_fma_f32 v[170:171], v[84:85], v[212:213], v[170:171]
	v_pk_fma_f32 v[164:165], v[78:79], v[182:183], v[164:165]
	v_pk_fma_f32 v[166:167], v[86:87], v[182:183], v[166:167]
	v_pk_fma_f32 v[168:169], v[78:79], v[214:215], v[168:169]
	v_pk_fma_f32 v[170:171], v[86:87], v[214:215], v[170:171]
	ds_read_b128 v[176:179], v2 offset:6912
	ds_read_b128 v[180:183], v2 offset:6928
	ds_read_b128 v[208:211], v2 offset:18944
	ds_read_b128 v[212:215], v2 offset:18960
	s_waitcnt lgkmcnt(9)
	v_pk_mul_f32 v[218:219], v[216:217], v[200:201] op_sel_hi:[0,1]
	v_pk_mul_f32 v[226:227], v[216:217], v[200:201] op_sel:[1,0]
	v_pk_mul_f32 v[220:221], v[216:217], v[202:203] op_sel_hi:[0,1]
	v_pk_mul_f32 v[228:229], v[216:217], v[202:203] op_sel:[1,0]
	v_pk_mul_f32 v[222:223], v[216:217], v[204:205] op_sel_hi:[0,1]
	v_pk_mul_f32 v[230:231], v[216:217], v[204:205] op_sel:[1,0]
	v_pk_mul_f32 v[224:225], v[216:217], v[206:207] op_sel_hi:[0,1]
	v_pk_mul_f32 v[234:235], v[216:217], v[206:207] op_sel:[1,0]
	ds_read_b128 v[200:203], v2 offset:15104
	ds_read_b128 v[204:207], v2 offset:15120
	ds_read_b64 v[216:217], v3 offset:43776
	v_add_f32_e32 v172, v164, v165
	v_add_f32_e32 v174, v166, v167
	v_add_f32_e32 v160, v168, v169
	v_add_f32_e32 v161, v170, v171
	s_waitcnt lgkmcnt(11)
	v_pk_fma_f32 v[218:219], v[72:73], v[184:185], v[218:219]
	v_pk_fma_f32 v[226:227], v[80:81], v[184:185], v[226:227]
	v_pk_fma_f32 v[220:221], v[74:75], v[186:187], v[220:221]
	v_pk_fma_f32 v[228:229], v[82:83], v[186:187], v[228:229]
	v_add_f32_dpp v172, v172, v172 quad_perm:[1,0,3,2] row_mask:0xf bank_mask:0xf bound_ctrl:1
	v_add_f32_dpp v174, v174, v174 quad_perm:[1,0,3,2] row_mask:0xf bank_mask:0xf bound_ctrl:1
	v_add_f32_dpp v160, v160, v160 quad_perm:[1,0,3,2] row_mask:0xf bank_mask:0xf bound_ctrl:1
	v_add_f32_dpp v161, v161, v161 quad_perm:[1,0,3,2] row_mask:0xf bank_mask:0xf bound_ctrl:1
	s_waitcnt lgkmcnt(10)
	v_pk_fma_f32 v[222:223], v[76:77], v[188:189], v[222:223]
	v_pk_fma_f32 v[230:231], v[84:85], v[188:189], v[230:231]
	v_pk_fma_f32 v[224:225], v[78:79], v[190:191], v[224:225]
	v_pk_fma_f32 v[234:235], v[86:87], v[190:191], v[234:235]
	ds_read_b128 v[184:187], v2 offset:2816
	ds_read_b128 v[188:191], v2 offset:2832
	v_add_f32_dpp v172, v172, v172 quad_perm:[2,3,0,1] row_mask:0xf bank_mask:0xf bound_ctrl:1
	v_add_f32_dpp v174, v174, v174 quad_perm:[2,3,0,1] row_mask:0xf bank_mask:0xf bound_ctrl:1
	v_add_f32_dpp v160, v160, v160 quad_perm:[2,3,0,1] row_mask:0xf bank_mask:0xf bound_ctrl:1
	v_add_f32_dpp v161, v161, v161 quad_perm:[2,3,0,1] row_mask:0xf bank_mask:0xf bound_ctrl:1
	v_add_f32_dpp v172, v172, v172 row_half_mirror row_mask:0xf bank_mask:0xf bound_ctrl:1
	v_add_f32_dpp v174, v174, v174 row_half_mirror row_mask:0xf bank_mask:0xf bound_ctrl:1
	v_add_f32_dpp v160, v160, v160 row_half_mirror row_mask:0xf bank_mask:0xf bound_ctrl:1
	v_add_f32_dpp v161, v161, v161 row_half_mirror row_mask:0xf bank_mask:0xf bound_ctrl:1
	s_waitcnt lgkmcnt(11)
	v_pk_fma_f32 v[72:73], v[192:193], v[172:173], v[218:219] op_sel_hi:[1,0,1]
	v_pk_fma_f32 v[80:81], v[192:193], v[174:175], v[226:227] op_sel_hi:[1,0,1]
	v_pk_fma_f32 v[74:75], v[194:195], v[172:173], v[220:221] op_sel_hi:[1,0,1]
	v_pk_fma_f32 v[82:83], v[194:195], v[174:175], v[228:229] op_sel_hi:[1,0,1]
	s_waitcnt lgkmcnt(10)
	v_pk_fma_f32 v[76:77], v[196:197], v[172:173], v[222:223] op_sel_hi:[1,0,1]
	v_pk_fma_f32 v[84:85], v[196:197], v[174:175], v[230:231] op_sel_hi:[1,0,1]
	v_pk_fma_f32 v[78:79], v[198:199], v[172:173], v[224:225] op_sel_hi:[1,0,1]
	v_pk_fma_f32 v[86:87], v[198:199], v[174:175], v[234:235] op_sel_hi:[1,0,1]
	ds_read_b128 v[192:195], v2 offset:11008
	ds_read_b128 v[196:199], v2 offset:11024
	ds_write_b64 v1, v[160:161] offset:56320
	s_waitcnt lgkmcnt(11)
	v_pk_mul_f32 v[164:165], v[72:73], v[176:177]
	v_pk_mul_f32 v[166:167], v[80:81], v[176:177]
	s_waitcnt lgkmcnt(9)
	v_pk_mul_f32 v[168:169], v[72:73], v[208:209]
	v_pk_mul_f32 v[170:171], v[80:81], v[208:209]
	v_pk_fma_f32 v[164:165], v[74:75], v[178:179], v[164:165]
	v_pk_fma_f32 v[166:167], v[82:83], v[178:179], v[166:167]
	v_pk_fma_f32 v[168:169], v[74:75], v[210:211], v[168:169]
	v_pk_fma_f32 v[170:171], v[82:83], v[210:211], v[170:171]
	v_pk_fma_f32 v[164:165], v[76:77], v[180:181], v[164:165]
	v_pk_fma_f32 v[166:167], v[84:85], v[180:181], v[166:167]
	s_waitcnt lgkmcnt(8)
	v_pk_fma_f32 v[168:169], v[76:77], v[212:213], v[168:169]
	v_pk_fma_f32 v[170:171], v[84:85], v[212:213], v[170:171]
	v_pk_fma_f32 v[164:165], v[78:79], v[182:183], v[164:165]
	v_pk_fma_f32 v[166:167], v[86:87], v[182:183], v[166:167]
	v_pk_fma_f32 v[168:169], v[78:79], v[214:215], v[168:169]
	v_pk_fma_f32 v[170:171], v[86:87], v[214:215], v[170:171]
	ds_read_b128 v[176:179], v2 offset:7168
	ds_read_b128 v[180:183], v2 offset:7184
	ds_read_b128 v[208:211], v2 offset:19200
	ds_read_b128 v[212:215], v2 offset:19216
	s_waitcnt lgkmcnt(9)
	v_pk_mul_f32 v[218:219], v[216:217], v[200:201] op_sel_hi:[0,1]
	v_pk_mul_f32 v[226:227], v[216:217], v[200:201] op_sel:[1,0]
	v_pk_mul_f32 v[220:221], v[216:217], v[202:203] op_sel_hi:[0,1]
	v_pk_mul_f32 v[228:229], v[216:217], v[202:203] op_sel:[1,0]
	v_pk_mul_f32 v[222:223], v[216:217], v[204:205] op_sel_hi:[0,1]
	v_pk_mul_f32 v[230:231], v[216:217], v[204:205] op_sel:[1,0]
	v_pk_mul_f32 v[224:225], v[216:217], v[206:207] op_sel_hi:[0,1]
	v_pk_mul_f32 v[234:235], v[216:217], v[206:207] op_sel:[1,0]
	ds_read_b128 v[200:203], v2 offset:15360
	ds_read_b128 v[204:207], v2 offset:15376
	ds_read_b64 v[216:217], v3 offset:44032
	v_add_f32_e32 v172, v164, v165
	v_add_f32_e32 v174, v166, v167
	v_add_f32_e32 v160, v168, v169
	v_add_f32_e32 v161, v170, v171
	s_waitcnt lgkmcnt(11)
	v_pk_fma_f32 v[218:219], v[72:73], v[184:185], v[218:219]
	v_pk_fma_f32 v[226:227], v[80:81], v[184:185], v[226:227]
	v_pk_fma_f32 v[220:221], v[74:75], v[186:187], v[220:221]
	v_pk_fma_f32 v[228:229], v[82:83], v[186:187], v[228:229]
	v_add_f32_dpp v172, v172, v172 quad_perm:[1,0,3,2] row_mask:0xf bank_mask:0xf bound_ctrl:1
	v_add_f32_dpp v174, v174, v174 quad_perm:[1,0,3,2] row_mask:0xf bank_mask:0xf bound_ctrl:1
	v_add_f32_dpp v160, v160, v160 quad_perm:[1,0,3,2] row_mask:0xf bank_mask:0xf bound_ctrl:1
	v_add_f32_dpp v161, v161, v161 quad_perm:[1,0,3,2] row_mask:0xf bank_mask:0xf bound_ctrl:1
	s_waitcnt lgkmcnt(10)
	v_pk_fma_f32 v[222:223], v[76:77], v[188:189], v[222:223]
	v_pk_fma_f32 v[230:231], v[84:85], v[188:189], v[230:231]
	v_pk_fma_f32 v[224:225], v[78:79], v[190:191], v[224:225]
	v_pk_fma_f32 v[234:235], v[86:87], v[190:191], v[234:235]
	ds_read_b128 v[184:187], v2 offset:3072
	ds_read_b128 v[188:191], v2 offset:3088
	v_add_f32_dpp v172, v172, v172 quad_perm:[2,3,0,1] row_mask:0xf bank_mask:0xf bound_ctrl:1
	v_add_f32_dpp v174, v174, v174 quad_perm:[2,3,0,1] row_mask:0xf bank_mask:0xf bound_ctrl:1
	v_add_f32_dpp v160, v160, v160 quad_perm:[2,3,0,1] row_mask:0xf bank_mask:0xf bound_ctrl:1
	v_add_f32_dpp v161, v161, v161 quad_perm:[2,3,0,1] row_mask:0xf bank_mask:0xf bound_ctrl:1
	v_add_f32_dpp v172, v172, v172 row_half_mirror row_mask:0xf bank_mask:0xf bound_ctrl:1
	v_add_f32_dpp v174, v174, v174 row_half_mirror row_mask:0xf bank_mask:0xf bound_ctrl:1
	v_add_f32_dpp v160, v160, v160 row_half_mirror row_mask:0xf bank_mask:0xf bound_ctrl:1
	v_add_f32_dpp v161, v161, v161 row_half_mirror row_mask:0xf bank_mask:0xf bound_ctrl:1
	s_waitcnt lgkmcnt(11)
	v_pk_fma_f32 v[72:73], v[192:193], v[172:173], v[218:219] op_sel_hi:[1,0,1]
	v_pk_fma_f32 v[80:81], v[192:193], v[174:175], v[226:227] op_sel_hi:[1,0,1]
	v_pk_fma_f32 v[74:75], v[194:195], v[172:173], v[220:221] op_sel_hi:[1,0,1]
	v_pk_fma_f32 v[82:83], v[194:195], v[174:175], v[228:229] op_sel_hi:[1,0,1]
	s_waitcnt lgkmcnt(10)
	v_pk_fma_f32 v[76:77], v[196:197], v[172:173], v[222:223] op_sel_hi:[1,0,1]
	v_pk_fma_f32 v[84:85], v[196:197], v[174:175], v[230:231] op_sel_hi:[1,0,1]
	v_pk_fma_f32 v[78:79], v[198:199], v[172:173], v[224:225] op_sel_hi:[1,0,1]
	v_pk_fma_f32 v[86:87], v[198:199], v[174:175], v[234:235] op_sel_hi:[1,0,1]
	ds_read_b128 v[192:195], v2 offset:11264
	ds_read_b128 v[196:199], v2 offset:11280
	ds_write_b64 v1, v[160:161] offset:56576
	s_waitcnt lgkmcnt(11)
	v_pk_mul_f32 v[164:165], v[72:73], v[176:177]
	v_pk_mul_f32 v[166:167], v[80:81], v[176:177]
	s_waitcnt lgkmcnt(9)
	v_pk_mul_f32 v[168:169], v[72:73], v[208:209]
	v_pk_mul_f32 v[170:171], v[80:81], v[208:209]
	v_pk_fma_f32 v[164:165], v[74:75], v[178:179], v[164:165]
	v_pk_fma_f32 v[166:167], v[82:83], v[178:179], v[166:167]
	v_pk_fma_f32 v[168:169], v[74:75], v[210:211], v[168:169]
	v_pk_fma_f32 v[170:171], v[82:83], v[210:211], v[170:171]
	v_pk_fma_f32 v[164:165], v[76:77], v[180:181], v[164:165]
	v_pk_fma_f32 v[166:167], v[84:85], v[180:181], v[166:167]
	s_waitcnt lgkmcnt(8)
	v_pk_fma_f32 v[168:169], v[76:77], v[212:213], v[168:169]
	v_pk_fma_f32 v[170:171], v[84:85], v[212:213], v[170:171]
	v_pk_fma_f32 v[164:165], v[78:79], v[182:183], v[164:165]
	v_pk_fma_f32 v[166:167], v[86:87], v[182:183], v[166:167]
	v_pk_fma_f32 v[168:169], v[78:79], v[214:215], v[168:169]
	v_pk_fma_f32 v[170:171], v[86:87], v[214:215], v[170:171]
	ds_read_b128 v[176:179], v2 offset:7424
	ds_read_b128 v[180:183], v2 offset:7440
	ds_read_b128 v[208:211], v2 offset:19456
	ds_read_b128 v[212:215], v2 offset:19472
	s_waitcnt lgkmcnt(9)
	v_pk_mul_f32 v[218:219], v[216:217], v[200:201] op_sel_hi:[0,1]
	v_pk_mul_f32 v[226:227], v[216:217], v[200:201] op_sel:[1,0]
	v_pk_mul_f32 v[220:221], v[216:217], v[202:203] op_sel_hi:[0,1]
	v_pk_mul_f32 v[228:229], v[216:217], v[202:203] op_sel:[1,0]
	v_pk_mul_f32 v[222:223], v[216:217], v[204:205] op_sel_hi:[0,1]
	v_pk_mul_f32 v[230:231], v[216:217], v[204:205] op_sel:[1,0]
	v_pk_mul_f32 v[224:225], v[216:217], v[206:207] op_sel_hi:[0,1]
	v_pk_mul_f32 v[234:235], v[216:217], v[206:207] op_sel:[1,0]
	ds_read_b128 v[200:203], v2 offset:15616
	ds_read_b128 v[204:207], v2 offset:15632
	ds_read_b64 v[216:217], v3 offset:44288
	v_add_f32_e32 v172, v164, v165
	v_add_f32_e32 v174, v166, v167
	v_add_f32_e32 v160, v168, v169
	v_add_f32_e32 v161, v170, v171
	s_waitcnt lgkmcnt(11)
	v_pk_fma_f32 v[218:219], v[72:73], v[184:185], v[218:219]
	v_pk_fma_f32 v[226:227], v[80:81], v[184:185], v[226:227]
	v_pk_fma_f32 v[220:221], v[74:75], v[186:187], v[220:221]
	v_pk_fma_f32 v[228:229], v[82:83], v[186:187], v[228:229]
	v_add_f32_dpp v172, v172, v172 quad_perm:[1,0,3,2] row_mask:0xf bank_mask:0xf bound_ctrl:1
	v_add_f32_dpp v174, v174, v174 quad_perm:[1,0,3,2] row_mask:0xf bank_mask:0xf bound_ctrl:1
	v_add_f32_dpp v160, v160, v160 quad_perm:[1,0,3,2] row_mask:0xf bank_mask:0xf bound_ctrl:1
	v_add_f32_dpp v161, v161, v161 quad_perm:[1,0,3,2] row_mask:0xf bank_mask:0xf bound_ctrl:1
	s_waitcnt lgkmcnt(10)
	v_pk_fma_f32 v[222:223], v[76:77], v[188:189], v[222:223]
	v_pk_fma_f32 v[230:231], v[84:85], v[188:189], v[230:231]
	v_pk_fma_f32 v[224:225], v[78:79], v[190:191], v[224:225]
	v_pk_fma_f32 v[234:235], v[86:87], v[190:191], v[234:235]
	ds_read_b128 v[184:187], v2 offset:3328
	ds_read_b128 v[188:191], v2 offset:3344
	v_add_f32_dpp v172, v172, v172 quad_perm:[2,3,0,1] row_mask:0xf bank_mask:0xf bound_ctrl:1
	v_add_f32_dpp v174, v174, v174 quad_perm:[2,3,0,1] row_mask:0xf bank_mask:0xf bound_ctrl:1
	v_add_f32_dpp v160, v160, v160 quad_perm:[2,3,0,1] row_mask:0xf bank_mask:0xf bound_ctrl:1
	v_add_f32_dpp v161, v161, v161 quad_perm:[2,3,0,1] row_mask:0xf bank_mask:0xf bound_ctrl:1
	v_add_f32_dpp v172, v172, v172 row_half_mirror row_mask:0xf bank_mask:0xf bound_ctrl:1
	v_add_f32_dpp v174, v174, v174 row_half_mirror row_mask:0xf bank_mask:0xf bound_ctrl:1
	v_add_f32_dpp v160, v160, v160 row_half_mirror row_mask:0xf bank_mask:0xf bound_ctrl:1
	v_add_f32_dpp v161, v161, v161 row_half_mirror row_mask:0xf bank_mask:0xf bound_ctrl:1
	s_waitcnt lgkmcnt(11)
	v_pk_fma_f32 v[72:73], v[192:193], v[172:173], v[218:219] op_sel_hi:[1,0,1]
	v_pk_fma_f32 v[80:81], v[192:193], v[174:175], v[226:227] op_sel_hi:[1,0,1]
	v_pk_fma_f32 v[74:75], v[194:195], v[172:173], v[220:221] op_sel_hi:[1,0,1]
	v_pk_fma_f32 v[82:83], v[194:195], v[174:175], v[228:229] op_sel_hi:[1,0,1]
	s_waitcnt lgkmcnt(10)
	v_pk_fma_f32 v[76:77], v[196:197], v[172:173], v[222:223] op_sel_hi:[1,0,1]
	v_pk_fma_f32 v[84:85], v[196:197], v[174:175], v[230:231] op_sel_hi:[1,0,1]
	v_pk_fma_f32 v[78:79], v[198:199], v[172:173], v[224:225] op_sel_hi:[1,0,1]
	v_pk_fma_f32 v[86:87], v[198:199], v[174:175], v[234:235] op_sel_hi:[1,0,1]
	ds_read_b128 v[192:195], v2 offset:11520
	ds_read_b128 v[196:199], v2 offset:11536
	ds_write_b64 v1, v[160:161] offset:56832
	s_waitcnt lgkmcnt(11)
	v_pk_mul_f32 v[164:165], v[72:73], v[176:177]
	v_pk_mul_f32 v[166:167], v[80:81], v[176:177]
	s_waitcnt lgkmcnt(9)
	v_pk_mul_f32 v[168:169], v[72:73], v[208:209]
	v_pk_mul_f32 v[170:171], v[80:81], v[208:209]
	v_pk_fma_f32 v[164:165], v[74:75], v[178:179], v[164:165]
	v_pk_fma_f32 v[166:167], v[82:83], v[178:179], v[166:167]
	v_pk_fma_f32 v[168:169], v[74:75], v[210:211], v[168:169]
	v_pk_fma_f32 v[170:171], v[82:83], v[210:211], v[170:171]
	v_pk_fma_f32 v[164:165], v[76:77], v[180:181], v[164:165]
	v_pk_fma_f32 v[166:167], v[84:85], v[180:181], v[166:167]
	s_waitcnt lgkmcnt(8)
	v_pk_fma_f32 v[168:169], v[76:77], v[212:213], v[168:169]
	v_pk_fma_f32 v[170:171], v[84:85], v[212:213], v[170:171]
	v_pk_fma_f32 v[164:165], v[78:79], v[182:183], v[164:165]
	v_pk_fma_f32 v[166:167], v[86:87], v[182:183], v[166:167]
	v_pk_fma_f32 v[168:169], v[78:79], v[214:215], v[168:169]
	v_pk_fma_f32 v[170:171], v[86:87], v[214:215], v[170:171]
	ds_read_b128 v[176:179], v2 offset:7680
	ds_read_b128 v[180:183], v2 offset:7696
	ds_read_b128 v[208:211], v2 offset:19712
	ds_read_b128 v[212:215], v2 offset:19728
	s_waitcnt lgkmcnt(9)
	v_pk_mul_f32 v[218:219], v[216:217], v[200:201] op_sel_hi:[0,1]
	v_pk_mul_f32 v[226:227], v[216:217], v[200:201] op_sel:[1,0]
	v_pk_mul_f32 v[220:221], v[216:217], v[202:203] op_sel_hi:[0,1]
	v_pk_mul_f32 v[228:229], v[216:217], v[202:203] op_sel:[1,0]
	v_pk_mul_f32 v[222:223], v[216:217], v[204:205] op_sel_hi:[0,1]
	v_pk_mul_f32 v[230:231], v[216:217], v[204:205] op_sel:[1,0]
	v_pk_mul_f32 v[224:225], v[216:217], v[206:207] op_sel_hi:[0,1]
	v_pk_mul_f32 v[234:235], v[216:217], v[206:207] op_sel:[1,0]
	ds_read_b128 v[200:203], v2 offset:15872
	ds_read_b128 v[204:207], v2 offset:15888
	ds_read_b64 v[216:217], v3 offset:44544
	v_add_f32_e32 v172, v164, v165
	v_add_f32_e32 v174, v166, v167
	v_add_f32_e32 v160, v168, v169
	v_add_f32_e32 v161, v170, v171
	s_waitcnt lgkmcnt(11)
	v_pk_fma_f32 v[218:219], v[72:73], v[184:185], v[218:219]
	v_pk_fma_f32 v[226:227], v[80:81], v[184:185], v[226:227]
	v_pk_fma_f32 v[220:221], v[74:75], v[186:187], v[220:221]
	v_pk_fma_f32 v[228:229], v[82:83], v[186:187], v[228:229]
	v_add_f32_dpp v172, v172, v172 quad_perm:[1,0,3,2] row_mask:0xf bank_mask:0xf bound_ctrl:1
	v_add_f32_dpp v174, v174, v174 quad_perm:[1,0,3,2] row_mask:0xf bank_mask:0xf bound_ctrl:1
	v_add_f32_dpp v160, v160, v160 quad_perm:[1,0,3,2] row_mask:0xf bank_mask:0xf bound_ctrl:1
	v_add_f32_dpp v161, v161, v161 quad_perm:[1,0,3,2] row_mask:0xf bank_mask:0xf bound_ctrl:1
	s_waitcnt lgkmcnt(10)
	v_pk_fma_f32 v[222:223], v[76:77], v[188:189], v[222:223]
	v_pk_fma_f32 v[230:231], v[84:85], v[188:189], v[230:231]
	v_pk_fma_f32 v[224:225], v[78:79], v[190:191], v[224:225]
	v_pk_fma_f32 v[234:235], v[86:87], v[190:191], v[234:235]
	ds_read_b128 v[184:187], v2 offset:3584
	ds_read_b128 v[188:191], v2 offset:3600
	v_add_f32_dpp v172, v172, v172 quad_perm:[2,3,0,1] row_mask:0xf bank_mask:0xf bound_ctrl:1
	v_add_f32_dpp v174, v174, v174 quad_perm:[2,3,0,1] row_mask:0xf bank_mask:0xf bound_ctrl:1
	v_add_f32_dpp v160, v160, v160 quad_perm:[2,3,0,1] row_mask:0xf bank_mask:0xf bound_ctrl:1
	v_add_f32_dpp v161, v161, v161 quad_perm:[2,3,0,1] row_mask:0xf bank_mask:0xf bound_ctrl:1
	v_add_f32_dpp v172, v172, v172 row_half_mirror row_mask:0xf bank_mask:0xf bound_ctrl:1
	v_add_f32_dpp v174, v174, v174 row_half_mirror row_mask:0xf bank_mask:0xf bound_ctrl:1
	v_add_f32_dpp v160, v160, v160 row_half_mirror row_mask:0xf bank_mask:0xf bound_ctrl:1
	v_add_f32_dpp v161, v161, v161 row_half_mirror row_mask:0xf bank_mask:0xf bound_ctrl:1
	s_waitcnt lgkmcnt(11)
	v_pk_fma_f32 v[72:73], v[192:193], v[172:173], v[218:219] op_sel_hi:[1,0,1]
	v_pk_fma_f32 v[80:81], v[192:193], v[174:175], v[226:227] op_sel_hi:[1,0,1]
	v_pk_fma_f32 v[74:75], v[194:195], v[172:173], v[220:221] op_sel_hi:[1,0,1]
	v_pk_fma_f32 v[82:83], v[194:195], v[174:175], v[228:229] op_sel_hi:[1,0,1]
	s_waitcnt lgkmcnt(10)
	v_pk_fma_f32 v[76:77], v[196:197], v[172:173], v[222:223] op_sel_hi:[1,0,1]
	v_pk_fma_f32 v[84:85], v[196:197], v[174:175], v[230:231] op_sel_hi:[1,0,1]
	v_pk_fma_f32 v[78:79], v[198:199], v[172:173], v[224:225] op_sel_hi:[1,0,1]
	v_pk_fma_f32 v[86:87], v[198:199], v[174:175], v[234:235] op_sel_hi:[1,0,1]
	ds_read_b128 v[192:195], v2 offset:11776
	ds_read_b128 v[196:199], v2 offset:11792
	ds_write_b64 v1, v[160:161] offset:57088
	s_waitcnt lgkmcnt(11)
	v_pk_mul_f32 v[164:165], v[72:73], v[176:177]
	v_pk_mul_f32 v[166:167], v[80:81], v[176:177]
	s_waitcnt lgkmcnt(9)
	v_pk_mul_f32 v[168:169], v[72:73], v[208:209]
	v_pk_mul_f32 v[170:171], v[80:81], v[208:209]
	v_pk_fma_f32 v[164:165], v[74:75], v[178:179], v[164:165]
	v_pk_fma_f32 v[166:167], v[82:83], v[178:179], v[166:167]
	v_pk_fma_f32 v[168:169], v[74:75], v[210:211], v[168:169]
	v_pk_fma_f32 v[170:171], v[82:83], v[210:211], v[170:171]
	v_pk_fma_f32 v[164:165], v[76:77], v[180:181], v[164:165]
	v_pk_fma_f32 v[166:167], v[84:85], v[180:181], v[166:167]
	s_waitcnt lgkmcnt(8)
	v_pk_fma_f32 v[168:169], v[76:77], v[212:213], v[168:169]
	v_pk_fma_f32 v[170:171], v[84:85], v[212:213], v[170:171]
	v_pk_fma_f32 v[164:165], v[78:79], v[182:183], v[164:165]
	v_pk_fma_f32 v[166:167], v[86:87], v[182:183], v[166:167]
	v_pk_fma_f32 v[168:169], v[78:79], v[214:215], v[168:169]
	v_pk_fma_f32 v[170:171], v[86:87], v[214:215], v[170:171]
	ds_read_b128 v[176:179], v2 offset:7936
	ds_read_b128 v[180:183], v2 offset:7952
	ds_read_b128 v[208:211], v2 offset:19968
	ds_read_b128 v[212:215], v2 offset:19984
	s_waitcnt lgkmcnt(9)
	v_pk_mul_f32 v[218:219], v[216:217], v[200:201] op_sel_hi:[0,1]
	v_pk_mul_f32 v[226:227], v[216:217], v[200:201] op_sel:[1,0]
	v_pk_mul_f32 v[220:221], v[216:217], v[202:203] op_sel_hi:[0,1]
	v_pk_mul_f32 v[228:229], v[216:217], v[202:203] op_sel:[1,0]
	v_pk_mul_f32 v[222:223], v[216:217], v[204:205] op_sel_hi:[0,1]
	v_pk_mul_f32 v[230:231], v[216:217], v[204:205] op_sel:[1,0]
	v_pk_mul_f32 v[224:225], v[216:217], v[206:207] op_sel_hi:[0,1]
	v_pk_mul_f32 v[234:235], v[216:217], v[206:207] op_sel:[1,0]
	ds_read_b128 v[200:203], v2 offset:16128
	ds_read_b128 v[204:207], v2 offset:16144
	ds_read_b64 v[216:217], v3 offset:44800
	v_add_f32_e32 v172, v164, v165
	v_add_f32_e32 v174, v166, v167
	v_add_f32_e32 v160, v168, v169
	v_add_f32_e32 v161, v170, v171
	s_waitcnt lgkmcnt(11)
	v_pk_fma_f32 v[218:219], v[72:73], v[184:185], v[218:219]
	v_pk_fma_f32 v[226:227], v[80:81], v[184:185], v[226:227]
	v_pk_fma_f32 v[220:221], v[74:75], v[186:187], v[220:221]
	v_pk_fma_f32 v[228:229], v[82:83], v[186:187], v[228:229]
	v_add_f32_dpp v172, v172, v172 quad_perm:[1,0,3,2] row_mask:0xf bank_mask:0xf bound_ctrl:1
	v_add_f32_dpp v174, v174, v174 quad_perm:[1,0,3,2] row_mask:0xf bank_mask:0xf bound_ctrl:1
	v_add_f32_dpp v160, v160, v160 quad_perm:[1,0,3,2] row_mask:0xf bank_mask:0xf bound_ctrl:1
	v_add_f32_dpp v161, v161, v161 quad_perm:[1,0,3,2] row_mask:0xf bank_mask:0xf bound_ctrl:1
	s_waitcnt lgkmcnt(10)
	v_pk_fma_f32 v[222:223], v[76:77], v[188:189], v[222:223]
	v_pk_fma_f32 v[230:231], v[84:85], v[188:189], v[230:231]
	v_pk_fma_f32 v[224:225], v[78:79], v[190:191], v[224:225]
	v_pk_fma_f32 v[234:235], v[86:87], v[190:191], v[234:235]
	ds_read_b128 v[184:187], v2 offset:3840
	ds_read_b128 v[188:191], v2 offset:3856
	v_add_f32_dpp v172, v172, v172 quad_perm:[2,3,0,1] row_mask:0xf bank_mask:0xf bound_ctrl:1
	v_add_f32_dpp v174, v174, v174 quad_perm:[2,3,0,1] row_mask:0xf bank_mask:0xf bound_ctrl:1
	v_add_f32_dpp v160, v160, v160 quad_perm:[2,3,0,1] row_mask:0xf bank_mask:0xf bound_ctrl:1
	v_add_f32_dpp v161, v161, v161 quad_perm:[2,3,0,1] row_mask:0xf bank_mask:0xf bound_ctrl:1
	v_add_f32_dpp v172, v172, v172 row_half_mirror row_mask:0xf bank_mask:0xf bound_ctrl:1
	v_add_f32_dpp v174, v174, v174 row_half_mirror row_mask:0xf bank_mask:0xf bound_ctrl:1
	v_add_f32_dpp v160, v160, v160 row_half_mirror row_mask:0xf bank_mask:0xf bound_ctrl:1
	v_add_f32_dpp v161, v161, v161 row_half_mirror row_mask:0xf bank_mask:0xf bound_ctrl:1
	s_waitcnt lgkmcnt(11)
	v_pk_fma_f32 v[72:73], v[192:193], v[172:173], v[218:219] op_sel_hi:[1,0,1]
	v_pk_fma_f32 v[80:81], v[192:193], v[174:175], v[226:227] op_sel_hi:[1,0,1]
	v_pk_fma_f32 v[74:75], v[194:195], v[172:173], v[220:221] op_sel_hi:[1,0,1]
	v_pk_fma_f32 v[82:83], v[194:195], v[174:175], v[228:229] op_sel_hi:[1,0,1]
	s_waitcnt lgkmcnt(10)
	v_pk_fma_f32 v[76:77], v[196:197], v[172:173], v[222:223] op_sel_hi:[1,0,1]
	v_pk_fma_f32 v[84:85], v[196:197], v[174:175], v[230:231] op_sel_hi:[1,0,1]
	v_pk_fma_f32 v[78:79], v[198:199], v[172:173], v[224:225] op_sel_hi:[1,0,1]
	v_pk_fma_f32 v[86:87], v[198:199], v[174:175], v[234:235] op_sel_hi:[1,0,1]
	ds_read_b128 v[192:195], v2 offset:12032
	ds_read_b128 v[196:199], v2 offset:12048
	ds_write_b64 v1, v[160:161] offset:57344
	s_waitcnt lgkmcnt(11)
	v_pk_mul_f32 v[164:165], v[72:73], v[176:177]
	v_pk_mul_f32 v[166:167], v[80:81], v[176:177]
	s_waitcnt lgkmcnt(9)
	v_pk_mul_f32 v[168:169], v[72:73], v[208:209]
	v_pk_mul_f32 v[170:171], v[80:81], v[208:209]
	v_pk_fma_f32 v[164:165], v[74:75], v[178:179], v[164:165]
	v_pk_fma_f32 v[166:167], v[82:83], v[178:179], v[166:167]
	v_pk_fma_f32 v[168:169], v[74:75], v[210:211], v[168:169]
	v_pk_fma_f32 v[170:171], v[82:83], v[210:211], v[170:171]
	v_pk_fma_f32 v[164:165], v[76:77], v[180:181], v[164:165]
	v_pk_fma_f32 v[166:167], v[84:85], v[180:181], v[166:167]
	s_waitcnt lgkmcnt(8)
	v_pk_fma_f32 v[168:169], v[76:77], v[212:213], v[168:169]
	v_pk_fma_f32 v[170:171], v[84:85], v[212:213], v[170:171]
	v_pk_fma_f32 v[164:165], v[78:79], v[182:183], v[164:165]
	v_pk_fma_f32 v[166:167], v[86:87], v[182:183], v[166:167]
	v_pk_fma_f32 v[168:169], v[78:79], v[214:215], v[168:169]
	v_pk_fma_f32 v[170:171], v[86:87], v[214:215], v[170:171]
	ds_read_b128 v[208:211], v2 offset:20224
	ds_read_b128 v[212:215], v2 offset:20240
	s_waitcnt lgkmcnt(7)
	v_pk_mul_f32 v[218:219], v[216:217], v[200:201] op_sel_hi:[0,1]
	v_pk_mul_f32 v[226:227], v[216:217], v[200:201] op_sel:[1,0]
	v_pk_mul_f32 v[220:221], v[216:217], v[202:203] op_sel_hi:[0,1]
	v_pk_mul_f32 v[228:229], v[216:217], v[202:203] op_sel:[1,0]
	v_pk_mul_f32 v[222:223], v[216:217], v[204:205] op_sel_hi:[0,1]
	v_pk_mul_f32 v[230:231], v[216:217], v[204:205] op_sel:[1,0]
	v_pk_mul_f32 v[224:225], v[216:217], v[206:207] op_sel_hi:[0,1]
	v_pk_mul_f32 v[234:235], v[216:217], v[206:207] op_sel:[1,0]
	v_add_f32_e32 v172, v164, v165
	v_add_f32_e32 v174, v166, v167
	v_add_f32_e32 v160, v168, v169
	v_add_f32_e32 v161, v170, v171
	s_waitcnt lgkmcnt(6)
	v_pk_fma_f32 v[218:219], v[72:73], v[184:185], v[218:219]
	v_pk_fma_f32 v[226:227], v[80:81], v[184:185], v[226:227]
	v_pk_fma_f32 v[220:221], v[74:75], v[186:187], v[220:221]
	v_pk_fma_f32 v[228:229], v[82:83], v[186:187], v[228:229]
	v_add_f32_dpp v172, v172, v172 quad_perm:[1,0,3,2] row_mask:0xf bank_mask:0xf bound_ctrl:1
	v_add_f32_dpp v174, v174, v174 quad_perm:[1,0,3,2] row_mask:0xf bank_mask:0xf bound_ctrl:1
	v_add_f32_dpp v160, v160, v160 quad_perm:[1,0,3,2] row_mask:0xf bank_mask:0xf bound_ctrl:1
	v_add_f32_dpp v161, v161, v161 quad_perm:[1,0,3,2] row_mask:0xf bank_mask:0xf bound_ctrl:1
	s_waitcnt lgkmcnt(5)
	v_pk_fma_f32 v[222:223], v[76:77], v[188:189], v[222:223]
	v_pk_fma_f32 v[230:231], v[84:85], v[188:189], v[230:231]
	v_pk_fma_f32 v[224:225], v[78:79], v[190:191], v[224:225]
	v_pk_fma_f32 v[234:235], v[86:87], v[190:191], v[234:235]
	v_add_f32_dpp v172, v172, v172 quad_perm:[2,3,0,1] row_mask:0xf bank_mask:0xf bound_ctrl:1
	v_add_f32_dpp v174, v174, v174 quad_perm:[2,3,0,1] row_mask:0xf bank_mask:0xf bound_ctrl:1
	v_add_f32_dpp v160, v160, v160 quad_perm:[2,3,0,1] row_mask:0xf bank_mask:0xf bound_ctrl:1
	v_add_f32_dpp v161, v161, v161 quad_perm:[2,3,0,1] row_mask:0xf bank_mask:0xf bound_ctrl:1
	v_add_f32_dpp v172, v172, v172 row_half_mirror row_mask:0xf bank_mask:0xf bound_ctrl:1
	v_add_f32_dpp v174, v174, v174 row_half_mirror row_mask:0xf bank_mask:0xf bound_ctrl:1
	v_add_f32_dpp v160, v160, v160 row_half_mirror row_mask:0xf bank_mask:0xf bound_ctrl:1
	v_add_f32_dpp v161, v161, v161 row_half_mirror row_mask:0xf bank_mask:0xf bound_ctrl:1
	s_waitcnt lgkmcnt(4)
	v_pk_fma_f32 v[72:73], v[192:193], v[172:173], v[218:219] op_sel_hi:[1,0,1]
	v_pk_fma_f32 v[80:81], v[192:193], v[174:175], v[226:227] op_sel_hi:[1,0,1]
	v_pk_fma_f32 v[74:75], v[194:195], v[172:173], v[220:221] op_sel_hi:[1,0,1]
	v_pk_fma_f32 v[82:83], v[194:195], v[174:175], v[228:229] op_sel_hi:[1,0,1]
	s_waitcnt lgkmcnt(3)
	v_pk_fma_f32 v[76:77], v[196:197], v[172:173], v[222:223] op_sel_hi:[1,0,1]
	v_pk_fma_f32 v[84:85], v[196:197], v[174:175], v[230:231] op_sel_hi:[1,0,1]
	v_pk_fma_f32 v[78:79], v[198:199], v[172:173], v[224:225] op_sel_hi:[1,0,1]
	v_pk_fma_f32 v[86:87], v[198:199], v[174:175], v[234:235] op_sel_hi:[1,0,1]
	ds_write_b64 v1, v[160:161] offset:57600
	s_waitcnt lgkmcnt(2)
	v_pk_mul_f32 v[168:169], v[72:73], v[208:209]
	v_pk_mul_f32 v[170:171], v[80:81], v[208:209]
	v_pk_fma_f32 v[168:169], v[74:75], v[210:211], v[168:169]
	v_pk_fma_f32 v[170:171], v[82:83], v[210:211], v[170:171]
	s_waitcnt lgkmcnt(1)
	v_pk_fma_f32 v[168:169], v[76:77], v[212:213], v[168:169]
	v_pk_fma_f32 v[170:171], v[84:85], v[212:213], v[170:171]
	v_pk_fma_f32 v[168:169], v[78:79], v[214:215], v[168:169]
	v_pk_fma_f32 v[170:171], v[86:87], v[214:215], v[170:171]
	s_nop 0
	v_add_f32_e32 v160, v168, v169
	v_add_f32_e32 v161, v170, v171
	s_nop 0
	v_add_f32_dpp v160, v160, v160 quad_perm:[1,0,3,2] row_mask:0xf bank_mask:0xf bound_ctrl:1
	v_add_f32_dpp v161, v161, v161 quad_perm:[1,0,3,2] row_mask:0xf bank_mask:0xf bound_ctrl:1
	s_nop 0
	v_add_f32_dpp v160, v160, v160 quad_perm:[2,3,0,1] row_mask:0xf bank_mask:0xf bound_ctrl:1
	v_add_f32_dpp v161, v161, v161 quad_perm:[2,3,0,1] row_mask:0xf bank_mask:0xf bound_ctrl:1
	s_nop 0
	v_add_f32_dpp v160, v160, v160 row_half_mirror row_mask:0xf bank_mask:0xf bound_ctrl:1
	v_add_f32_dpp v161, v161, v161 row_half_mirror row_mask:0xf bank_mask:0xf bound_ctrl:1
	s_nop 0
	ds_write_b64 v1, v[160:161] offset:57856
	s_add_i32 s3, s2, 1
	s_mov_b64 s[36:37], 0
.LBB0_391:
	s_andn2_b64 vcc, exec, s[36:37]
	s_cbranch_vccnz .LBB0_411
	s_add_i32 s3, s2, 1
	s_cmpk_eq_i32 s2, 0x7f
	s_cselect_b64 s[38:39], -1, 0
	s_cmpk_lg_i32 s2, 0x7f
	s_cselect_b64 s[50:51], -1, 0
	s_and_b64 vcc, exec, s[38:39]
	s_cbranch_vccnz .LBB0_394
	s_lshl_b32 s8, s3, 4
	s_or_b32 s26, s8, s96
	s_add_u32 s8, s30, s26
	s_addc_u32 s9, s31, 0
	s_mul_i32 s27, s9, 0xe00
	v_mad_u64_u32 v[2:3], s[24:25], s8, v240, v[70:71]
	s_lshl_b64 s[8:9], s[8:9], 9
	v_lshl_add_u64 v[8:9], s[8:9], 0, v[24:25]
	s_or_b32 s8, s26, 4
	s_add_u32 s8, s30, s8
	s_addc_u32 s9, s31, 0
	v_add_u32_e32 v3, s27, v3
	s_mul_i32 s27, s9, 0xe00
	v_mad_u64_u32 v[16:17], s[24:25], s8, v240, v[70:71]
	v_add_u32_e32 v17, s27, v17
	s_lshl_b64 s[8:9], s[8:9], 9
	global_load_ushort v176, v[16:17], off
	global_load_ushort v177, v[16:17], off offset:-3584
	global_load_ushort v178, v[16:17], off offset:-2560
	global_load_ushort v179, v[16:17], off offset:-1536
	global_load_ushort v180, v[2:3], off
	global_load_ushort v181, v[16:17], off offset:1024
	global_load_ushort v182, v[2:3], off offset:1024
	global_load_ushort v183, v[16:17], off offset:2048
	global_load_ushort v184, v[2:3], off offset:2048
	global_load_ushort v185, v[2:3], off offset:-3584
	global_load_ushort v186, v[2:3], off offset:-2560
	global_load_ushort v187, v[2:3], off offset:-1536
	v_lshl_add_u64 v[2:3], s[8:9], 0, v[24:25]
	s_or_b32 s8, s26, 8
	s_add_u32 s36, s30, s8
	s_addc_u32 s37, s31, 0
	s_lshl_b64 s[8:9], s[36:37], 9
	v_lshl_add_u64 v[26:27], s[8:9], 0, v[24:25]
	s_or_b32 s8, s26, 12
	s_add_u32 s52, s30, s8
	s_addc_u32 s53, s31, 0
	s_lshl_b64 s[8:9], s[52:53], 9
	v_lshlrev_b64 v[8:9], 1, v[8:9]
	v_lshlrev_b64 v[2:3], 1, v[2:3]
	v_lshl_add_u64 v[30:31], s[8:9], 0, v[24:25]
	v_lshl_add_u64 v[10:11], s[20:21], 0, v[8:9]
	v_lshl_add_u64 v[16:17], s[20:21], 0, v[2:3]
	v_lshl_add_u64 v[2:3], s[22:23], 0, v[2:3]
	v_lshlrev_b64 v[26:27], 1, v[26:27]
	v_lshlrev_b64 v[30:31], 1, v[30:31]
	v_lshl_add_u64 v[8:9], s[22:23], 0, v[8:9]
	v_lshl_add_u64 v[28:29], s[20:21], 0, v[26:27]
	v_lshl_add_u64 v[26:27], s[22:23], 0, v[26:27]
	v_lshl_add_u64 v[32:33], s[20:21], 0, v[30:31]
	v_lshl_add_u64 v[30:31], s[22:23], 0, v[30:31]
	global_load_ushort v188, v[16:17], off
	s_nop 0
	global_load_ushort v189, v[10:11], off
	s_nop 0
	global_load_ushort v190, v[2:3], off
	global_load_ushort v191, v[28:29], off
	global_load_ushort v192, v[26:27], off
	global_load_ushort v193, v[32:33], off
	global_load_ushort v194, v[30:31], off
	global_load_ushort v195, v[8:9], off
	s_mul_i32 s24, s37, 0xe00
	v_mad_u64_u32 v[2:3], s[8:9], s36, v240, v[70:71]
	v_add_u32_e32 v3, s24, v3
	s_mul_i32 s24, s53, 0xe00
	v_mad_u64_u32 v[8:9], s[8:9], s52, v240, v[70:71]
	v_add_u32_e32 v9, s24, v9
	global_load_ushort v196, v[2:3], off
	global_load_ushort v197, v[8:9], off
	global_load_ushort v198, v[2:3], off offset:1024
	global_load_ushort v199, v[8:9], off offset:1024
	global_load_ushort v200, v[2:3], off offset:2048
	global_load_ushort v201, v[8:9], off offset:2048
	global_load_ushort v202, v[2:3], off offset:-3584
	global_load_ushort v203, v[8:9], off offset:-3584
	global_load_ushort v204, v[2:3], off offset:-2560
	global_load_ushort v205, v[8:9], off offset:-2560
	s_nop 0
	global_load_ushort v206, v[2:3], off offset:-1536
	s_nop 0
	global_load_ushort v207, v[8:9], off offset:-1536
.LBB0_394:
	s_cmp_lg_u32 s2, 0
	s_cselect_b64 s[36:37], -1, 0
	s_cmp_eq_u32 s2, 0
	s_mov_b32 s8, 0
	s_cbranch_scc1 .LBB0_396
	s_lshl_b32 s8, s2, 4
	s_add_i32 s9, s8, -16
	s_add_u32 s24, s34, s9
	s_addc_u32 s25, s35, 0
	s_lshl_b64 s[24:25], s[24:25], 10
	v_lshl_add_u64 v[2:3], v[62:63], 0, s[24:25]
	v_add_co_u32_e32 v4, vcc, 0x1000, v2
	global_load_ushort v208, v[2:3], off
	s_nop 0
	v_addc_co_u32_e32 v5, vcc, 0, v3, vcc
	global_load_ushort v209, v[4:5], off
	v_add_co_u32_e32 v4, vcc, 0x2000, v2
	s_nop 1
	v_addc_co_u32_e32 v5, vcc, 0, v3, vcc
	v_add_co_u32_e32 v2, vcc, 0x3000, v2
	global_load_ushort v210, v[4:5], off
	s_nop 0
	v_addc_co_u32_e32 v3, vcc, 0, v3, vcc
	global_load_ushort v211, v[2:3], off

.LBB0_398:
	s_or_b64 exec, exec, s[38:39]
	v_lshl_or_b32 v2, s8, 10, v142
	v_mov_b32_e32 v3, v0
	v_lshl_add_u64 v[2:3], v[68:69], 0, v[2:3]
	global_load_ushort v212, v[2:3], off
	global_load_ushort v213, v[2:3], off offset:1024
	global_load_ushort v214, v[2:3], off offset:2048
	global_load_ushort v215, v[2:3], off offset:3072
	v_add_u32_e32 v91, v143, v102
	ds_read_b128 v[92:95], v91 offset:12544
	ds_read_b128 v[164:167], v91 offset:13056
	s_waitcnt lgkmcnt(1)
	v_mfma_f32_16x16x32_bf16 v[92:95], v[12:15], v[92:95], 0
	v_add_u32_e32 v96, 0xf000, v138
	v_add_u32_e32 v97, 0xf400, v138
	v_add_u32_e32 v159, 0xf800, v138
	s_waitcnt lgkmcnt(0)
	v_mfma_f32_16x16x32_bf16 v[164:167], v[12:15], v[164:167], 0
	s_andn2_b64 vcc, exec, s[50:51]
	s_nop 6
	ds_write2_b32 v96, v92, v164 offset0:192 offset1:208
	ds_write2_b32 v97, v93, v165 offset0:64 offset1:80
	ds_write2_b32 v97, v94, v166 offset0:192 offset1:208
	ds_write2_b32 v159, v95, v167 offset0:64 offset1:80
	ds_read_b128 v[92:95], v91 offset:13568
	ds_read_b128 v[164:167], v146 offset:12544
	s_waitcnt lgkmcnt(1)
	v_mfma_f32_16x16x32_bf16 v[92:95], v[12:15], v[92:95], 0
	s_waitcnt lgkmcnt(0)
	v_mfma_f32_16x16x32_bf16 v[164:167], v[12:15], v[164:167], 0
	s_nop 7
	ds_write2_b32 v96, v92, v164 offset0:224 offset1:240
	ds_write2_b32 v97, v93, v165 offset0:96 offset1:112
	ds_write2_b32 v97, v94, v166 offset0:224 offset1:240
	ds_write2_b32 v159, v95, v167 offset0:96 offset1:112
	ds_read_b128 v[92:95], v91 offset:14592
	ds_read_b128 v[164:167], v91 offset:15104
	s_waitcnt lgkmcnt(1)
	v_mfma_f32_16x16x32_bf16 v[92:95], v[12:15], v[92:95], 0
	s_waitcnt lgkmcnt(0)
	v_mfma_f32_16x16x32_bf16 v[164:167], v[12:15], v[164:167], 0
	s_nop 7
	ds_write2_b32 v97, v92, v164 offset1:16
	ds_write2_b32 v97, v93, v165 offset0:128 offset1:144
	ds_write2_b32 v159, v94, v166 offset1:16
	ds_write2_b32 v159, v95, v167 offset0:128 offset1:144
	ds_read_b128 v[92:95], v91 offset:15616
	ds_read_b128 v[164:167], v147 offset:12544
	s_waitcnt lgkmcnt(1)
	v_mfma_f32_16x16x32_bf16 v[92:95], v[12:15], v[92:95], 0
	s_waitcnt lgkmcnt(0)
	v_mfma_f32_16x16x32_bf16 v[12:15], v[12:15], v[164:167], 0
	s_nop 7
	ds_write2_b32 v97, v92, v12 offset0:32 offset1:48
	ds_write2_b32 v97, v93, v13 offset0:160 offset1:176
	ds_write2_b32 v159, v94, v14 offset0:32 offset1:48
	ds_write2_b32 v159, v95, v15 offset0:160 offset1:176
	s_waitcnt lgkmcnt(0)
	ds_read2st64_b32 v[12:13], v139 offset0:243 offset1:244
	v_pk_mul_f32 v[14:15], v[56:57], v[60:61]
	s_nop 0
	v_sub_f32_e32 v14, v14, v15
	s_waitcnt lgkmcnt(0)
	v_add_f32_e32 v12, v14, v12
	v_pk_mul_f32 v[14:15], v[56:57], v[60:61] op_sel:[0,1] op_sel_hi:[1,0]
	ds_read2st64_b32 v[60:61], v139 offset0:245 offset1:246
	v_add_f32_e32 v14, v14, v15
	v_add_f32_e32 v14, v14, v13
	v_cvt_pk_bf16_f32 v13, v12, v0
	ds_write_b16 v141, v13 offset:8192
	v_cvt_pk_bf16_f32 v13, v14, v0
	v_pk_mul_f32 v[14:15], v[64:65], v[14:15] op_sel_hi:[1,0]
	ds_write_b16 v141, v13 offset:8320
	v_pk_fma_f32 v[92:93], v[56:57], v[12:13], v[14:15] neg_lo:[0,0,1] neg_hi:[0,0,1]
	v_pk_fma_f32 v[12:13], v[56:57], v[12:13], v[14:15] op_sel_hi:[1,0,1]
	s_nop 0
	v_mov_b32_e32 v93, v13
	s_waitcnt lgkmcnt(2)
	v_pk_add_f32 v[12:13], v[92:93], v[60:61]
	s_nop 0
	v_cvt_pk_bf16_f32 v14, v12, v0
	ds_write_b16 v141, v14 offset:8464
	v_cvt_pk_bf16_f32 v14, v13, v0
	ds_write_b16 v141, v14 offset:8592
	ds_read2st64_b32 v[14:15], v139 offset0:247 offset1:248
	v_pk_mul_f32 v[60:61], v[56:57], v[12:13]
	v_pk_mul_f32 v[12:13], v[64:65], v[12:13]
	v_sub_f32_e32 v60, v60, v61
	v_add_f32_e32 v12, v12, v13
	s_waitcnt lgkmcnt(0)
	v_add_f32_e32 v14, v60, v14
	v_cvt_pk_bf16_f32 v13, v14, v0
	ds_read2st64_b32 v[60:61], v139 offset0:249 offset1:250
	v_add_f32_e32 v12, v12, v15
	ds_write_b16 v141, v13 offset:8736
	v_cvt_pk_bf16_f32 v13, v12, v0
	ds_write_b16 v141, v13 offset:8864
	v_pk_mul_f32 v[12:13], v[64:65], v[12:13] op_sel_hi:[1,0]
	s_nop 0
	v_pk_fma_f32 v[92:93], v[56:57], v[14:15], v[12:13] neg_lo:[0,0,1] neg_hi:[0,0,1]
	v_pk_fma_f32 v[12:13], v[56:57], v[14:15], v[12:13] op_sel_hi:[1,0,1]
	s_nop 0
	v_mov_b32_e32 v93, v13
	s_waitcnt lgkmcnt(2)
	v_pk_add_f32 v[12:13], v[92:93], v[60:61]
	s_nop 0
	v_cvt_pk_bf16_f32 v14, v12, v0
	ds_write_b16 v141, v14 offset:9008
	v_cvt_pk_bf16_f32 v14, v13, v0
	ds_write_b16 v141, v14 offset:9136
	ds_read2st64_b32 v[14:15], v139 offset0:251 offset1:252
	v_pk_mul_f32 v[60:61], v[56:57], v[12:13]
	v_pk_mul_f32 v[12:13], v[64:65], v[12:13]
	v_sub_f32_e32 v60, v60, v61
	v_add_f32_e32 v12, v12, v13
	s_waitcnt lgkmcnt(0)
	v_add_f32_e32 v14, v60, v14
	v_cvt_pk_bf16_f32 v13, v14, v0
	ds_read2st64_b32 v[60:61], v139 offset0:253 offset1:254
	v_add_f32_e32 v12, v12, v15
	ds_write_b16 v141, v13 offset:9280
	v_cvt_pk_bf16_f32 v13, v12, v0
	ds_write_b16 v141, v13 offset:9408
	v_pk_mul_f32 v[12:13], v[64:65], v[12:13] op_sel_hi:[1,0]
	s_nop 0
	v_pk_fma_f32 v[92:93], v[56:57], v[14:15], v[12:13] neg_lo:[0,0,1] neg_hi:[0,0,1]
	v_pk_fma_f32 v[12:13], v[56:57], v[14:15], v[12:13] op_sel_hi:[1,0,1]
	s_nop 0
	v_mov_b32_e32 v93, v13
	s_waitcnt lgkmcnt(2)
	v_pk_add_f32 v[12:13], v[92:93], v[60:61]
	s_nop 0
	v_cvt_pk_bf16_f32 v14, v12, v0
	ds_write_b16 v141, v14 offset:9552
	v_cvt_pk_bf16_f32 v14, v13, v0
	ds_write_b16 v141, v14 offset:9680
	ds_read_b32 v91, v139 offset:65280
	ds_read2st64_b32 v[14:15], v140 offset0:13 offset1:14
	v_pk_mul_f32 v[60:61], v[56:57], v[12:13]
	v_pk_mul_f32 v[12:13], v[64:65], v[12:13]
	v_sub_f32_e32 v60, v60, v61
	ds_read2st64_b32 v[92:93], v140 offset0:15 offset1:16
	s_waitcnt lgkmcnt(2)
	v_add_f32_e32 v60, v60, v91
	v_add_f32_e32 v12, v12, v13
	v_cvt_pk_bf16_f32 v13, v60, v0
	s_waitcnt lgkmcnt(1)
	v_add_f32_e32 v12, v12, v14
	ds_write_b16 v141, v13 offset:9824
	v_cvt_pk_bf16_f32 v13, v12, v0
	ds_write_b16 v141, v13 offset:9952
	v_pk_mul_f32 v[12:13], v[64:65], v[12:13] op_sel_hi:[1,0]
	s_nop 0
	v_pk_fma_f32 v[94:95], v[56:57], v[60:61], v[12:13] neg_lo:[0,0,1] neg_hi:[0,0,1]
	v_pk_fma_f32 v[12:13], v[56:57], v[60:61], v[12:13] op_sel_hi:[1,0,1]
	s_nop 0
	v_mov_b32_e32 v95, v13
	v_mov_b32_e32 v12, v15
	s_waitcnt lgkmcnt(2)
	v_mov_b32_e32 v13, v92
	v_pk_add_f32 v[12:13], v[94:95], v[12:13]
	s_nop 0
	v_cvt_pk_bf16_f32 v14, v12, v0
	ds_write_b16 v141, v14 offset:10096
	v_cvt_pk_bf16_f32 v14, v13, v0
	ds_write_b16 v141, v14 offset:10224
	ds_read2st64_b32 v[14:15], v140 offset0:17 offset1:18
	v_pk_mul_f32 v[60:61], v[56:57], v[12:13]
	v_pk_mul_f32 v[12:13], v[64:65], v[12:13]
	v_sub_f32_e32 v60, v60, v61
	v_add_f32_e32 v60, v60, v93
	ds_read2st64_b32 v[92:93], v140 offset0:19 offset1:20
	v_add_f32_e32 v12, v12, v13
	v_cvt_pk_bf16_f32 v13, v60, v0
	s_waitcnt lgkmcnt(1)
	v_add_f32_e32 v12, v12, v14
	ds_write_b16 v141, v13 offset:10368
	v_cvt_pk_bf16_f32 v13, v12, v0
	ds_write_b16 v141, v13 offset:10496
	v_pk_mul_f32 v[12:13], v[64:65], v[12:13] op_sel_hi:[1,0]
	s_nop 0
	v_pk_fma_f32 v[94:95], v[56:57], v[60:61], v[12:13] neg_lo:[0,0,1] neg_hi:[0,0,1]
	v_pk_fma_f32 v[12:13], v[56:57], v[60:61], v[12:13] op_sel_hi:[1,0,1]
	s_nop 0
	v_mov_b32_e32 v95, v13
	v_mov_b32_e32 v12, v15
	s_waitcnt lgkmcnt(2)
	v_mov_b32_e32 v13, v92
	v_pk_add_f32 v[12:13], v[94:95], v[12:13]
	s_nop 0
	v_cvt_pk_bf16_f32 v14, v12, v0
	ds_write_b16 v141, v14 offset:10640
	v_cvt_pk_bf16_f32 v14, v13, v0
	ds_write_b16 v141, v14 offset:10768
	ds_read2st64_b32 v[14:15], v140 offset0:21 offset1:22
	v_pk_mul_f32 v[60:61], v[56:57], v[12:13]
	v_pk_mul_f32 v[12:13], v[64:65], v[12:13]
	v_sub_f32_e32 v60, v60, v61
	v_add_f32_e32 v60, v60, v93
	ds_read2st64_b32 v[92:93], v140 offset0:23 offset1:24
	v_add_f32_e32 v12, v12, v13
	v_cvt_pk_bf16_f32 v13, v60, v0
	s_waitcnt lgkmcnt(1)
	v_add_f32_e32 v12, v12, v14
	ds_write_b16 v141, v13 offset:10912
	v_cvt_pk_bf16_f32 v13, v12, v0
	ds_write_b16 v141, v13 offset:11040
	v_pk_mul_f32 v[12:13], v[64:65], v[12:13] op_sel_hi:[1,0]
	s_nop 0
	v_pk_fma_f32 v[94:95], v[56:57], v[60:61], v[12:13] neg_lo:[0,0,1] neg_hi:[0,0,1]
	v_pk_fma_f32 v[12:13], v[56:57], v[60:61], v[12:13] op_sel_hi:[1,0,1]
	s_nop 0
	v_mov_b32_e32 v95, v13
	v_mov_b32_e32 v12, v15
	s_waitcnt lgkmcnt(2)
	v_mov_b32_e32 v13, v92
	v_pk_add_f32 v[12:13], v[94:95], v[12:13]
	s_nop 0
	v_cvt_pk_bf16_f32 v14, v12, v0
	ds_write_b16 v141, v14 offset:11184
	v_cvt_pk_bf16_f32 v14, v13, v0
	ds_write_b16 v141, v14 offset:11312
	ds_read2st64_b32 v[14:15], v140 offset0:25 offset1:26
	v_pk_mul_f32 v[60:61], v[56:57], v[12:13]
	v_pk_mul_f32 v[12:13], v[64:65], v[12:13]
	v_sub_f32_e32 v60, v60, v61
	v_add_f32_e32 v60, v60, v93
	ds_read2st64_b32 v[92:93], v140 offset0:27 offset1:28
	v_add_f32_e32 v12, v12, v13
	v_cvt_pk_bf16_f32 v13, v60, v0
	s_waitcnt lgkmcnt(1)
	v_add_f32_e32 v12, v12, v14
	ds_write_b16 v141, v13 offset:11456
	v_cvt_pk_bf16_f32 v13, v12, v0
	ds_write_b16 v141, v13 offset:11584
	v_pk_mul_f32 v[12:13], v[64:65], v[12:13] op_sel_hi:[1,0]
	s_nop 0
	v_pk_fma_f32 v[94:95], v[56:57], v[60:61], v[12:13] neg_lo:[0,0,1] neg_hi:[0,0,1]
	v_pk_fma_f32 v[12:13], v[56:57], v[60:61], v[12:13] op_sel_hi:[1,0,1]
	s_nop 0
	v_mov_b32_e32 v95, v13
	v_mov_b32_e32 v12, v15
	s_waitcnt lgkmcnt(2)
	v_mov_b32_e32 v13, v92
	v_pk_add_f32 v[12:13], v[94:95], v[12:13]
	s_nop 0
	v_cvt_pk_bf16_f32 v14, v12, v0
	ds_write_b16 v141, v14 offset:11728
	v_cvt_pk_bf16_f32 v14, v13, v0
	ds_write_b16 v141, v14 offset:11856
	ds_read2st64_b32 v[14:15], v140 offset0:29 offset1:30
	v_pk_mul_f32 v[60:61], v[56:57], v[12:13]
	v_pk_mul_f32 v[12:13], v[64:65], v[12:13]
	v_sub_f32_e32 v60, v60, v61
	v_add_f32_e32 v60, v60, v93
	v_add_f32_e32 v12, v12, v13
	v_cvt_pk_bf16_f32 v13, v60, v0
	s_waitcnt lgkmcnt(0)
	v_add_f32_e32 v12, v12, v14
	ds_write_b16 v141, v13 offset:12000
	v_cvt_pk_bf16_f32 v13, v12, v0
	ds_write_b16 v141, v13 offset:12128
	ds_read_b32 v13, v140 offset:7936
	s_waitcnt lgkmcnt(0)
	v_pk_mul_f32 v[92:93], v[64:65], v[12:13] op_sel_hi:[1,0]
	s_nop 0
	v_pk_fma_f32 v[94:95], v[56:57], v[60:61], v[92:93] neg_lo:[0,0,1] neg_hi:[0,0,1]
	v_pk_fma_f32 v[60:61], v[56:57], v[60:61], v[92:93] op_sel_hi:[1,0,1]
	v_mov_b32_e32 v12, v15
	v_mov_b32_e32 v95, v61
	v_pk_add_f32 v[60:61], v[94:95], v[12:13]
	s_nop 0
	v_cvt_pk_bf16_f32 v12, v60, v0
	ds_write_b16 v141, v12 offset:12272
	v_cvt_pk_bf16_f32 v12, v61, v0
	ds_write_b16 v141, v12 offset:12400
	s_waitcnt lgkmcnt(0)
	ds_read_b128 v[12:15], v144 offset:8192
	ds_read_b128 v[92:95], v145 offset:16640
	s_waitcnt lgkmcnt(0)
	v_mfma_f32_16x16x32_bf16 v[12:15], v[12:15], v[92:95], 0
	ds_read_b128 v[92:95], v144 offset:8256
	ds_read_b128 v[164:167], v145 offset:16704
	s_waitcnt lgkmcnt(0)
	v_mfma_f32_16x16x32_bf16 v[12:15], v[92:95], v[164:167], v[12:15]
	ds_read_b128 v[92:95], v144 offset:8320
	ds_read_b128 v[164:167], v145 offset:16768
	s_waitcnt lgkmcnt(0)
	v_mfma_f32_16x16x32_bf16 v[12:15], v[92:95], v[164:167], v[12:15]
	ds_read_b128 v[92:95], v144 offset:8384
	ds_read_b128 v[164:167], v145 offset:16832
	s_waitcnt lgkmcnt(0)
	v_mfma_f32_16x16x32_bf16 v[12:15], v[92:95], v[164:167], v[12:15]
	s_nop 7
	s_waitcnt vmcnt(0)
	v_lshlrev_b32_e32 v90, 16, v212
	v_lshlrev_b32_e32 v89, 16, v213
	v_lshlrev_b32_e32 v88, 16, v214
	v_lshlrev_b32_e32 v1, 16, v215
	v_fma_f32 v12, v148, v90, v12
	v_mul_f32_e32 v90, 0x3d372713, v12
	v_mul_f32_e32 v90, v12, v90
	v_fma_f32 v90, v12, v90, v12
	v_mul_f32_e32 v90, 0x3f4c422a, v90
	v_add_f32_e32 v90, v90, v90
	v_mul_f32_e32 v90, 0x3fb8aa3b, v90
	v_exp_f32_e32 v90, v90
	v_mul_f32_e32 v12, 0.5, v12
	v_fmac_f32_e32 v15, v148, v1
	v_mul_f32_e32 v1, 0x3d372713, v15
	v_add_f32_e32 v90, 1.0, v90
	v_rcp_f32_e32 v90, v90
	v_mul_f32_e32 v1, v15, v1
	v_fma_f32 v1, v15, v1, v15
	v_mul_f32_e32 v1, 0x3f4c422a, v1
	v_fma_f32 v90, v90, -2.0, 1.0
	v_add_f32_e32 v90, 1.0, v90
	v_mul_f32_e32 v12, v12, v90
	v_cvt_pk_bf16_f32 v12, v12, v0
	global_store_short v[2:3], v12, off
	v_fma_f32 v12, v148, v89, v13
	v_mul_f32_e32 v13, 0x3d372713, v12
	v_mul_f32_e32 v13, v12, v13
	v_fma_f32 v13, v12, v13, v12
	v_mul_f32_e32 v13, 0x3f4c422a, v13
	v_add_f32_e32 v13, v13, v13
	v_mul_f32_e32 v13, 0x3fb8aa3b, v13
	v_exp_f32_e32 v13, v13
	v_mul_f32_e32 v12, 0.5, v12
	v_add_f32_e32 v1, v1, v1
	v_mul_f32_e32 v1, 0x3fb8aa3b, v1
	v_add_f32_e32 v13, 1.0, v13
	v_rcp_f32_e32 v13, v13
	v_exp_f32_e32 v1, v1
	v_fma_f32 v13, v13, -2.0, 1.0
	v_add_f32_e32 v13, 1.0, v13
	v_mul_f32_e32 v12, v12, v13
	v_cvt_pk_bf16_f32 v12, v12, v0
	global_store_short v[2:3], v12, off offset:1024
	v_fma_f32 v12, v148, v88, v14
	v_mul_f32_e32 v13, 0x3d372713, v12
	v_mul_f32_e32 v13, v12, v13
	v_fma_f32 v13, v12, v13, v12
	v_mul_f32_e32 v13, 0x3f4c422a, v13
	v_add_f32_e32 v13, v13, v13
	v_mul_f32_e32 v13, 0x3fb8aa3b, v13
	v_exp_f32_e32 v13, v13
	v_add_f32_e32 v1, 1.0, v1
	v_rcp_f32_e32 v1, v1
	v_mul_f32_e32 v12, 0.5, v12
	v_add_f32_e32 v13, 1.0, v13
	v_rcp_f32_e32 v13, v13
	v_fma_f32 v1, v1, -2.0, 1.0
	v_add_f32_e32 v1, 1.0, v1
	v_fma_f32 v13, v13, -2.0, 1.0
	v_add_f32_e32 v13, 1.0, v13
	v_mul_f32_e32 v12, v12, v13
	v_cvt_pk_bf16_f32 v12, v12, v0
	global_store_short v[2:3], v12, off offset:2048
	v_mul_f32_e32 v12, 0.5, v15
	v_mul_f32_e32 v1, v12, v1
	v_cvt_pk_bf16_f32 v1, v1, v0
	global_store_short v[2:3], v1, off offset:3072
	s_waitcnt lgkmcnt(0)
	v_lshlrev_b32_e32 v1, 2, v128
	s_cbranch_vccnz .LBB0_408
	s_waitcnt vmcnt(4)
	v_lshlrev_b32_e32 v16, 16, v176
	v_lshlrev_b32_e32 v30, 16, v177
	v_lshlrev_b32_e32 v32, 16, v178
	v_lshlrev_b32_e32 v36, 16, v179
	v_lshlrev_b32_e32 v17, 16, v180
	v_lshlrev_b32_e32 v26, 16, v181
	v_lshlrev_b32_e32 v27, 16, v182
	v_lshlrev_b32_e32 v28, 16, v183
	v_lshlrev_b32_e32 v29, 16, v184
	v_lshlrev_b32_e32 v31, 16, v185
	v_lshlrev_b32_e32 v33, 16, v186
	v_lshlrev_b32_e32 v37, 16, v187
	v_lshlrev_b32_e32 v34, 16, v188
	v_lshlrev_b32_e32 v35, 16, v189
	v_lshlrev_b32_e32 v38, 16, v190
	v_lshlrev_b32_e32 v39, 16, v195
	v_lshlrev_b32_e32 v40, 16, v197
	v_lshlrev_b32_e32 v43, 16, v198
	v_lshlrev_b32_e32 v42, 16, v199
	v_lshlrev_b32_e32 v45, 16, v200
	v_lshlrev_b32_e32 v44, 16, v201
	v_lshlrev_b32_e32 v46, 16, v203
	v_lshlrev_b32_e32 v49, 16, v204
	v_lshlrev_b32_e32 v48, 16, v205
	v_lshlrev_b32_e32 v41, 16, v196
	v_lshlrev_b32_e32 v47, 16, v202
	v_lshlrev_b32_e32 v51, 16, v206
	v_lshlrev_b32_e32 v50, 16, v207
	v_lshlrev_b32_e32 v53, 16, v191
	v_lshlrev_b32_e32 v52, 16, v193
	v_lshlrev_b32_e32 v55, 16, v192
	v_lshlrev_b32_e32 v54, 16, v194
	v_add_f32_e32 v88, v155, v35
	v_mul_f32_e32 v88, 0xbfb8aa3b, v88
	v_exp_f32_e32 v88, v88
	v_pk_add_f32 v[12:13], v[32:33], v[26:27] neg_lo:[0,1] neg_hi:[0,1]
	v_pk_add_f32 v[2:3], v[30:31], v[16:17] neg_lo:[0,1] neg_hi:[0,1]
	v_fma_f32 v13, v150, v13, v27
	v_add_f32_e32 v88, 1.0, v88
	v_rcp_f32_e32 v88, v88
	v_mul_f32_e32 v92, v157, v13
	v_fma_f32 v3, v149, v3, v17
	s_bitcmp1_b32 s3, 0
	v_mul_f32_e32 v89, 0xbf6002b1, v88
	v_cmp_gt_f32_e32 vcc, s85, v89
	s_cselect_b32 s8, 0x5000, 0
	v_mov_b32_e32 v94, v0
	v_cndmask_b32_e32 v89, 0, v239, vcc
	v_fmac_f32_e32 v89, 0xbf6002b1, v88
	v_exp_f32_e32 v88, v89
	v_cndmask_b32_e32 v89, 0, v236, vcc
	s_add_i32 s9, s8, 0
	s_mul_i32 s8, s3, 0xab
	v_ldexp_f32 v90, v88, v89
	v_add_f32_e32 v88, v154, v39
	v_mul_f32_e32 v88, 0xbfb8aa3b, v88
	v_exp_f32_e32 v88, v88
	v_mov_b32_e32 v89, v0
	s_bfe_u32 s8, s8, 0x70009
	s_mul_i32 s8, s8, 3
	v_add_f32_e32 v88, 1.0, v88
	v_rcp_f32_e32 v91, v88
	v_mul_f32_e32 v88, v92, v92
	s_sub_i32 s8, s3, s8
	s_and_b32 s8, s8, 0xff
	v_mov_b32_dpp v89, v88 quad_perm:[1,0,3,2] row_mask:0xf bank_mask:0xf
	v_fmac_f32_e32 v89, v92, v92
	s_mulk_i32 s8, 0x1100
	s_add_i32 s8, s8, 0
	v_add_f32_dpp v88, v89, v89 quad_perm:[2,3,0,1] row_mask:0xf bank_mask:0xf bound_ctrl:1
	v_pk_add_f32 v[14:15], v[36:37], v[28:29] neg_lo:[0,1] neg_hi:[0,1]
	s_nop 0
	v_add_f32_dpp v88, v88, v88 row_half_mirror row_mask:0xf bank_mask:0xf bound_ctrl:1
	v_fma_f32 v15, v151, v15, v29
	s_nop 0
	v_add_f32_dpp v88, v88, v88 row_mirror row_mask:0xf bank_mask:0xf bound_ctrl:1
	s_nop 0
	v_readlane_b32 s26, v88, 16
	v_readlane_b32 s27, v88, 48
	v_readlane_b32 s24, v88, 0
	v_readlane_b32 s25, v88, 32
	v_mov_b32_e32 v88, s26
	v_mov_b32_e32 v89, s27
	v_pk_add_f32 v[88:89], s[24:25], v[88:89]
	s_nop 0
	v_add_f32_e32 v88, v88, v89
	v_add_f32_e32 v88, 0x2b8cbccc, v88
	v_cmp_gt_f32_e32 vcc, s82, v88
	v_mul_f32_e32 v89, 0x4b800000, v88
	s_nop 0
	v_cndmask_b32_e32 v88, v88, v89, vcc
	v_rsq_f32_e32 v88, v88
	s_nop 0
	v_mul_f32_e32 v89, 0x45800000, v88
	v_cndmask_b32_e32 v88, v88, v89, vcc
	v_add_f32_e32 v89, -1.0, v91
	v_fma_f32 v89, v158, v89, 1.0
	v_mul_f32_e32 v13, v89, v13
	v_mul_f32_e32 v89, v13, v3
	v_mul_f32_e32 v93, v156, v89
	v_mul_f32_e64 v88, v92, -v88
	s_nop 0
	v_mov_b32_dpp v94, v93 quad_perm:[1,0,3,2] row_mask:0xf bank_mask:0xf
	v_fmac_f32_e32 v94, v156, v89
	s_nop 1
	v_add_f32_dpp v89, v94, v94 quad_perm:[2,3,0,1] row_mask:0xf bank_mask:0xf bound_ctrl:1
	s_nop 1
	v_add_f32_dpp v89, v89, v89 row_half_mirror row_mask:0xf bank_mask:0xf bound_ctrl:1
	s_nop 1
	v_add_f32_dpp v89, v89, v89 row_mirror row_mask:0xf bank_mask:0xf bound_ctrl:1
	s_nop 0
	v_readlane_b32 s38, v89, 0
	v_readlane_b32 s52, v89, 16
	v_readlane_b32 s39, v89, 32
	v_readlane_b32 s53, v89, 48
	v_add_u32_e32 v89, s9, v1
	ds_write2st64_b32 v89, v90, v88 offset1:16
	v_mul_f32_e64 v88, v91, -v88
	ds_write2st64_b32 v89, v88, v13 offset0:32 offset1:48
	ds_write_b32 v89, v3 offset:16384
	v_add_u32_e32 v3, s8, v1
	ds_write_b32 v3, v15 offset:40960
	s_and_saveexec_b64 s[50:51], s[44:45]
	s_cbranch_execz .LBB0_401
	s_lshl_b32 s24, s96, 2
	v_mov_b32_e32 v88, s52
	v_mov_b32_e32 v89, s53
	s_add_i32 s24, s8, s24
	v_pk_add_f32 v[88:89], s[38:39], v[88:89]
	v_mov_b32_e32 v13, s24
	v_add_f32_e32 v3, v88, v89
	ds_write_b32 v13, v3 offset:45056

.LBB0_408:
	s_andn2_b64 vcc, exec, s[36:37]
	s_mov_b32 s8, 1
	s_cbranch_vccnz .LBB0_410
	s_waitcnt vmcnt(4)
	v_lshlrev_b32_e32 v4, 16, v208
	v_lshlrev_b32_e32 v5, 16, v209
	v_lshlrev_b32_e32 v6, 16, v210
	v_lshlrev_b32_e32 v7, 16, v211
	s_add_i32 s8, s2, -1
	s_and_b32 s2, s8, 0xff
	s_mulk_i32 s2, 0xab
	s_lshr_b32 s2, s2, 9
	s_mul_i32 s2, s2, 3
	s_sub_i32 s2, s8, s2
	s_and_b32 s2, s2, 0xff
	s_lshl_b32 s9, s8, 12
	s_mulk_i32 s2, 0x1100
	s_and_b32 s9, s9, 0x1000
	s_add_i32 s2, s2, 0
	s_add_i32 s9, s9, 0
	v_lshlrev_b32_e32 v15, 2, v134
	v_add_u32_e32 v2, s9, v1
	v_add_u32_e32 v1, s2, v1
	v_lshlrev_b32_e32 v3, 2, v130
	v_lshlrev_b32_e32 v13, 2, v132
	v_add_u32_e32 v88, s9, v15
	v_add_u32_e32 v12, s9, v3
	v_add_u32_e32 v3, s2, v3
	v_add_u32_e32 v14, s9, v13
	v_add_u32_e32 v13, s2, v13
	v_add_u32_e32 v15, s2, v15
	ds_read_b32 v89, v2 offset:54016
	ds_read_b32 v1, v1 offset:40960
	ds_read_b32 v90, v12 offset:54016
	ds_read_b32 v91, v3 offset:40960
	ds_read_b32 v92, v14 offset:54016
	ds_read_b32 v93, v13 offset:40960
	ds_read_b32 v88, v88 offset:54016
	ds_read_b32 v94, v15 offset:40960
	s_waitcnt lgkmcnt(7)
	v_add_f32_dpp v2, v89, v89 quad_perm:[1,0,3,2] row_mask:0xf bank_mask:0xf bound_ctrl:1
	s_lshl_b32 s8, s8, 4
	s_add_u32 s36, s30, s8
	v_add_f32_dpp v2, v2, v2 quad_perm:[2,3,0,1] row_mask:0xf bank_mask:0xf bound_ctrl:1
	s_addc_u32 s37, s31, 0
	s_nop 0
	v_add_f32_dpp v2, v2, v2 row_half_mirror row_mask:0xf bank_mask:0xf bound_ctrl:1
	s_nop 1
	v_add_f32_dpp v2, v2, v2 row_mirror row_mask:0xf bank_mask:0xf bound_ctrl:1
	s_nop 0
	v_readlane_b32 s9, v2, 16
	v_readlane_b32 s26, v2, 48
	v_readlane_b32 s24, v2, 0
	v_readlane_b32 s25, v2, 32
	v_mov_b32_e32 v2, s9
	v_mov_b32_e32 v3, s26
	v_pk_add_f32 v[2:3], s[24:25], v[2:3]
	s_nop 0
	v_add_f32_e32 v2, v2, v3
	v_fmac_f32_e32 v89, 0xbc800000, v2
	v_mul_f32_e32 v2, v89, v89
	v_mov_b32_e32 v3, v0
	s_nop 1
	v_mov_b32_dpp v3, v2 quad_perm:[1,0,3,2] row_mask:0xf bank_mask:0xf
	v_fmac_f32_e32 v3, v89, v89
	s_nop 1
	v_add_f32_dpp v2, v3, v3 quad_perm:[2,3,0,1] row_mask:0xf bank_mask:0xf bound_ctrl:1
	s_nop 1
	v_add_f32_dpp v2, v2, v2 row_half_mirror row_mask:0xf bank_mask:0xf bound_ctrl:1
	s_nop 1
	v_add_f32_dpp v2, v2, v2 row_mirror row_mask:0xf bank_mask:0xf bound_ctrl:1
	s_nop 0
	v_readlane_b32 s9, v2, 16
	v_readlane_b32 s26, v2, 48
	v_readlane_b32 s24, v2, 0
	v_readlane_b32 s25, v2, 32
	v_mov_b32_e32 v2, s9
	v_mov_b32_e32 v3, s26
	v_pk_add_f32 v[2:3], s[24:25], v[2:3]
	s_lshl_b32 s24, s96, 2
	v_add_f32_e32 v2, v2, v3
	v_fmamk_f32 v2, v2, 0x3c800000, v233
	v_mul_f32_e32 v3, 0x4b800000, v2
	v_cmp_gt_f32_e32 vcc, s82, v2
	s_add_i32 s2, s2, s24
	s_or_b64 s[8:9], s[36:37], s[96:97]
	v_cndmask_b32_e32 v2, v2, v3, vcc
	v_rsq_f32_e32 v12, v2
	v_mov_b32_e32 v2, s2
	v_add_u32_e32 v14, 0xb000, v2
	ds_read2_b32 v[2:3], v14 offset1:4
	v_mul_f32_e32 v13, 0x45800000, v12
	v_cndmask_b32_e32 v12, v12, v13, vcc
	v_mul_f32_e32 v12, v89, v12
	v_fma_f32 v15, v153, v12, v152
	s_waitcnt lgkmcnt(0)
	v_fmac_f32_e32 v15, v2, v1
	v_add_f32_dpp v2, v90, v90 quad_perm:[1,0,3,2] row_mask:0xf bank_mask:0xf bound_ctrl:1
	ds_read2_b32 v[12:13], v14 offset0:8 offset1:12
	v_mul_f32_e32 v1, v4, v15
	v_add_f32_dpp v2, v2, v2 quad_perm:[2,3,0,1] row_mask:0xf bank_mask:0xf bound_ctrl:1
	s_lshl_b64 s[8:9], s[8:9], 10
	v_cvt_pk_bf16_f32 v1, v1, v0
	s_nop 0
	v_add_f32_dpp v2, v2, v2 row_half_mirror row_mask:0xf bank_mask:0xf bound_ctrl:1
	s_nop 1
	v_add_f32_dpp v2, v2, v2 row_mirror row_mask:0xf bank_mask:0xf bound_ctrl:1
	s_nop 0
	v_readlane_b32 s2, v2, 16
	v_readlane_b32 s26, v2, 48
	v_readlane_b32 s24, v2, 0
	v_readlane_b32 s25, v2, 32
	v_mov_b32_e32 v14, s2
	v_mov_b32_e32 v15, s26
	v_pk_add_f32 v[14:15], s[24:25], v[14:15]
	s_nop 0
	v_add_f32_e32 v2, v14, v15
	v_fmac_f32_e32 v90, 0xbc800000, v2
	v_mul_f32_e32 v2, v90, v90
	v_mov_b32_e32 v14, v0
	s_nop 1
	v_mov_b32_dpp v14, v2 quad_perm:[1,0,3,2] row_mask:0xf bank_mask:0xf
	v_fmac_f32_e32 v14, v90, v90
	s_nop 1
	v_add_f32_dpp v2, v14, v14 quad_perm:[2,3,0,1] row_mask:0xf bank_mask:0xf bound_ctrl:1
	s_nop 1
	v_add_f32_dpp v2, v2, v2 row_half_mirror row_mask:0xf bank_mask:0xf bound_ctrl:1
	s_nop 1
	v_add_f32_dpp v2, v2, v2 row_mirror row_mask:0xf bank_mask:0xf bound_ctrl:1
	s_nop 0
	v_readlane_b32 s2, v2, 16
	v_readlane_b32 s26, v2, 48
	v_readlane_b32 s24, v2, 0
	v_readlane_b32 s25, v2, 32
	v_mov_b32_e32 v14, s2
	v_mov_b32_e32 v15, s26
	v_pk_add_f32 v[14:15], s[24:25], v[14:15]
	s_nop 0
	v_add_f32_e32 v2, v14, v15
	v_fmamk_f32 v2, v2, 0x3c800000, v233
	v_mul_f32_e32 v14, 0x4b800000, v2
	v_cmp_gt_f32_e32 vcc, s82, v2
	s_nop 1
	v_cndmask_b32_e32 v2, v2, v14, vcc
	v_rsq_f32_e32 v2, v2
	v_lshl_add_u64 v[14:15], v[58:59], 0, s[8:9]
	global_store_short v[14:15], v1, off
	s_or_b64 s[8:9], s[36:37], s[12:13]
	v_mul_f32_e32 v1, 0x45800000, v2
	v_cndmask_b32_e32 v1, v2, v1, vcc
	v_add_f32_dpp v2, v92, v92 quad_perm:[1,0,3,2] row_mask:0xf bank_mask:0xf bound_ctrl:1
	v_mul_f32_e32 v1, v90, v1
	v_fma_f32 v1, v153, v1, v152
	v_add_f32_dpp v2, v2, v2 quad_perm:[2,3,0,1] row_mask:0xf bank_mask:0xf bound_ctrl:1
	v_fmac_f32_e32 v1, v3, v91
	s_lshl_b64 s[8:9], s[8:9], 10
	v_add_f32_dpp v2, v2, v2 row_half_mirror row_mask:0xf bank_mask:0xf bound_ctrl:1
	v_mul_f32_e32 v1, v5, v1
	v_cvt_pk_bf16_f32 v1, v1, v0
	s_nop 0
	v_add_f32_dpp v2, v2, v2 row_mirror row_mask:0xf bank_mask:0xf bound_ctrl:1
	s_nop 0
	v_readlane_b32 s2, v2, 16
	v_readlane_b32 s26, v2, 48
	v_readlane_b32 s24, v2, 0
	v_readlane_b32 s25, v2, 32
	v_mov_b32_e32 v2, s2
	v_mov_b32_e32 v3, s26
	v_pk_add_f32 v[2:3], s[24:25], v[2:3]
	s_nop 0
	v_add_f32_e32 v2, v2, v3
	v_fmac_f32_e32 v92, 0xbc800000, v2
	v_mul_f32_e32 v2, v92, v92
	v_mov_b32_e32 v3, v0
	s_nop 1
	v_mov_b32_dpp v3, v2 quad_perm:[1,0,3,2] row_mask:0xf bank_mask:0xf
	v_fmac_f32_e32 v3, v92, v92
	s_nop 1
	v_add_f32_dpp v2, v3, v3 quad_perm:[2,3,0,1] row_mask:0xf bank_mask:0xf bound_ctrl:1
	s_nop 1
	v_add_f32_dpp v2, v2, v2 row_half_mirror row_mask:0xf bank_mask:0xf bound_ctrl:1
	s_nop 1
	v_add_f32_dpp v2, v2, v2 row_mirror row_mask:0xf bank_mask:0xf bound_ctrl:1
	s_nop 0
	v_readlane_b32 s2, v2, 16
	v_readlane_b32 s26, v2, 48
	v_readlane_b32 s24, v2, 0
	v_readlane_b32 s25, v2, 32
	v_mov_b32_e32 v2, s2
	v_mov_b32_e32 v3, s26
	v_pk_add_f32 v[2:3], s[24:25], v[2:3]
	s_nop 0
	v_add_f32_e32 v2, v2, v3
	v_fmamk_f32 v2, v2, 0x3c800000, v233
	v_mul_f32_e32 v3, 0x4b800000, v2
	v_cmp_gt_f32_e32 vcc, s82, v2
	s_nop 1
	v_cndmask_b32_e32 v2, v2, v3, vcc
	v_rsq_f32_e32 v14, v2
	v_lshl_add_u64 v[2:3], v[58:59], 0, s[8:9]
	global_store_short v[2:3], v1, off
	s_or_b64 s[8:9], s[36:37], s[14:15]
	v_add_f32_dpp v2, v88, v88 quad_perm:[1,0,3,2] row_mask:0xf bank_mask:0xf bound_ctrl:1
	v_mul_f32_e32 v1, 0x45800000, v14
	v_cndmask_b32_e32 v1, v14, v1, vcc
	v_add_f32_dpp v2, v2, v2 quad_perm:[2,3,0,1] row_mask:0xf bank_mask:0xf bound_ctrl:1
	v_mul_f32_e32 v1, v92, v1
	v_fma_f32 v1, v153, v1, v152
	v_add_f32_dpp v2, v2, v2 row_half_mirror row_mask:0xf bank_mask:0xf bound_ctrl:1
	s_waitcnt lgkmcnt(0)
	v_fmac_f32_e32 v1, v12, v93
	v_mul_f32_e32 v1, v6, v1
	v_add_f32_dpp v2, v2, v2 row_mirror row_mask:0xf bank_mask:0xf bound_ctrl:1
	s_lshl_b64 s[8:9], s[8:9], 10
	v_readlane_b32 s2, v2, 16
	v_readlane_b32 s26, v2, 48
	v_readlane_b32 s24, v2, 0
	v_readlane_b32 s25, v2, 32
	v_mov_b32_e32 v2, s2
	v_mov_b32_e32 v3, s26
	v_pk_add_f32 v[2:3], s[24:25], v[2:3]
	v_cvt_pk_bf16_f32 v1, v1, v0
	s_nop 0
	v_add_f32_e32 v2, v2, v3
	v_fmac_f32_e32 v88, 0xbc800000, v2
	v_mul_f32_e32 v2, v88, v88
	v_mov_b32_e32 v3, v0
	s_nop 1
	v_mov_b32_dpp v3, v2 quad_perm:[1,0,3,2] row_mask:0xf bank_mask:0xf
	v_fmac_f32_e32 v3, v88, v88
	s_nop 1
	v_add_f32_dpp v2, v3, v3 quad_perm:[2,3,0,1] row_mask:0xf bank_mask:0xf bound_ctrl:1
	s_nop 1
	v_add_f32_dpp v2, v2, v2 row_half_mirror row_mask:0xf bank_mask:0xf bound_ctrl:1
	s_nop 1
	v_add_f32_dpp v2, v2, v2 row_mirror row_mask:0xf bank_mask:0xf bound_ctrl:1
	s_nop 0
	v_readlane_b32 s2, v2, 16
	v_readlane_b32 s26, v2, 48
	v_readlane_b32 s24, v2, 0
	v_readlane_b32 s25, v2, 32
	v_mov_b32_e32 v2, s2
	v_mov_b32_e32 v3, s26
	v_pk_add_f32 v[2:3], s[24:25], v[2:3]
	s_nop 0
	v_add_f32_e32 v2, v2, v3
	v_fmamk_f32 v2, v2, 0x3c800000, v233
	v_mul_f32_e32 v3, 0x4b800000, v2
	v_cmp_gt_f32_e32 vcc, s82, v2
	s_nop 1
	v_cndmask_b32_e32 v2, v2, v3, vcc
	v_rsq_f32_e32 v12, v2
	v_lshl_add_u64 v[2:3], v[58:59], 0, s[8:9]
	global_store_short v[2:3], v1, off
	s_or_b64 s[8:9], s[36:37], s[16:17]
	v_mul_f32_e32 v1, 0x45800000, v12
	v_cndmask_b32_e32 v1, v12, v1, vcc
	v_mul_f32_e32 v1, v88, v1
	v_fma_f32 v1, v153, v1, v152
	v_fmac_f32_e32 v1, v13, v94
	s_lshl_b64 s[8:9], s[8:9], 10
	v_mul_f32_e32 v1, v7, v1
	v_lshl_add_u64 v[2:3], v[58:59], 0, s[8:9]
	s_mov_b32 s8, s3
	v_cvt_pk_bf16_f32 v1, v1, v0
	global_store_short v[2:3], v1, off

.LBB0_411:
	s_mov_b32 s2, s3
